# cv42 + GEMM K-loops: the LDS-DMA operand loads of every load segment are issued before that segment's ds_read fragment loads (DMA latency chain starts earlier)
# baseline (speedup 1.0000x reference)
.LBB0_306:
	s_add_u32 s38, s36, 0xfff80080
	s_addc_u32 s39, s37, -1
	s_add_i32 s45, 0, 0x10000
	s_cmp_eq_u32 s27, 28
	s_cselect_b32 s43, s9, s39
	s_cselect_b32 s42, s14, s38
	v_add_u32_e32 v34, s45, v170
	s_cselect_b32 s39, s16, s26
	s_cselect_b32 s38, s17, s25
	s_add_i32 s47, 0, 0x14000
	s_add_i32 m0, s35, 0xc000
	global_load_lds_dwordx4 v152, s[36:37]
	s_add_i32 m0, s35, 0xe000
	s_nop 0
	global_load_lds_dwordx4 v156, s[36:37]
	ds_read_b128 v[160:163], v34
	ds_read_b128 v[164:167], v34 offset:1024
	ds_read_b128 v[174:177], v34 offset:2048
	ds_read_b128 v[184:187], v34 offset:3072
	v_add_u32_e32 v34, s47, v170
	ds_read_b128 v[188:191], v34
	ds_read_b128 v[192:195], v34 offset:1024
	ds_read_b128 v[196:199], v34 offset:2048
	ds_read_b128 v[200:203], v34 offset:3072
	ds_read_b128 v[214:217], v173
	ds_read_b128 v[218:221], v173 offset:1024
	ds_read_b128 v[222:225], v173 offset:2048
	ds_read_b128 v[226:229], v173 offset:3072
	ds_read_b128 v[230:233], v173 offset:4096
	ds_read_b128 v[234:237], v173 offset:5120
	ds_read_b128 v[238:241], v173 offset:6144
	ds_read_b128 v[242:245], v173 offset:7168
	s_waitcnt vmcnt(8)
	s_waitcnt lgkmcnt(0)
	s_barrier
	s_setprio 1
	s_waitcnt lgkmcnt(0)
	v_mfma_f32_16x16x32_bf16 v[132:135], v[160:163], v[214:217], v[132:135]
	v_mfma_f32_16x16x32_bf16 v[128:131], v[174:177], v[214:217], v[128:131]
	v_mfma_f32_16x16x32_bf16 v[116:119], v[160:163], v[222:225], v[116:119]
	v_mfma_f32_16x16x32_bf16 v[112:115], v[174:177], v[222:225], v[112:115]
	v_mfma_f32_16x16x32_bf16 v[100:103], v[160:163], v[230:233], v[100:103]
	v_mfma_f32_16x16x32_bf16 v[96:99], v[174:177], v[230:233], v[96:99]
	v_mfma_f32_16x16x32_bf16 v[84:87], v[160:163], v[238:241], v[84:87]
	v_mfma_f32_16x16x32_bf16 v[80:83], v[174:177], v[238:241], v[80:83]
	v_mfma_f32_16x16x32_bf16 v[132:135], v[164:167], v[218:221], v[132:135]
	v_mfma_f32_16x16x32_bf16 v[128:131], v[184:187], v[218:221], v[128:131]
	v_mfma_f32_16x16x32_bf16 v[116:119], v[164:167], v[226:229], v[116:119]
	v_mfma_f32_16x16x32_bf16 v[112:115], v[184:187], v[226:229], v[112:115]
	v_mfma_f32_16x16x32_bf16 v[100:103], v[164:167], v[234:237], v[100:103]
	v_mfma_f32_16x16x32_bf16 v[96:99], v[184:187], v[234:237], v[96:99]
	v_mfma_f32_16x16x32_bf16 v[84:87], v[164:167], v[242:245], v[84:87]
	v_mfma_f32_16x16x32_bf16 v[80:83], v[184:187], v[242:245], v[80:83]
	s_setprio 0
	s_setprio 1
	v_mfma_f32_16x16x32_bf16 v[124:127], v[188:191], v[214:217], v[124:127]
	v_mfma_f32_16x16x32_bf16 v[120:123], v[196:199], v[214:217], v[120:123]
	v_mfma_f32_16x16x32_bf16 v[108:111], v[188:191], v[222:225], v[108:111]
	v_mfma_f32_16x16x32_bf16 v[104:107], v[196:199], v[222:225], v[104:107]
	v_mfma_f32_16x16x32_bf16 v[92:95], v[188:191], v[230:233], v[92:95]
	v_mfma_f32_16x16x32_bf16 v[88:91], v[196:199], v[230:233], v[88:91]
	v_mfma_f32_16x16x32_bf16 v[76:79], v[188:191], v[238:241], v[76:79]
	v_mfma_f32_16x16x32_bf16 v[72:75], v[196:199], v[238:241], v[72:75]
	v_mfma_f32_16x16x32_bf16 v[124:127], v[192:195], v[218:221], v[124:127]
	v_mfma_f32_16x16x32_bf16 v[120:123], v[200:203], v[218:221], v[120:123]
	v_mfma_f32_16x16x32_bf16 v[108:111], v[192:195], v[226:229], v[108:111]
	v_mfma_f32_16x16x32_bf16 v[104:107], v[200:203], v[226:229], v[104:107]
	v_mfma_f32_16x16x32_bf16 v[92:95], v[192:195], v[234:237], v[92:95]
	v_mfma_f32_16x16x32_bf16 v[88:91], v[200:203], v[234:237], v[88:91]
	v_mfma_f32_16x16x32_bf16 v[76:79], v[192:195], v[242:245], v[76:79]
	v_mfma_f32_16x16x32_bf16 v[72:75], v[200:203], v[242:245], v[72:75]
	s_setprio 0
	s_barrier
	s_add_u32 s98, s38, s22
	s_addc_u32 s99, s39, s23
	s_add_u32 s100, s42, s22
	s_addc_u32 s101, s43, s23
	s_add_i32 s45, s45, s53
	s_mov_b32 m0, s45
	global_load_lds_dwordx4 v136, s[38:39]
	s_add_i32 m0, s45, 0x2000
	s_add_u32 s70, s38, 0x80000
	s_addc_u32 s71, s39, 0
	s_add_i32 s45, s47, s53
	global_load_lds_dwordx4 v140, s[38:39]
	s_mov_b32 m0, s45
	global_load_lds_dwordx4 v136, s[70:71]
	s_add_i32 m0, s45, 0x2000
	s_nop 0
	global_load_lds_dwordx4 v140, s[70:71]
	s_mov_b32 m0, s35
	s_nop 0
	global_load_lds_dwordx4 v14, s[42:43]
	s_mov_b32 m0, s54
	s_nop 0
	global_load_lds_dwordx4 v138, s[42:43]
	ds_read_b128 v[214:217], v173 offset:16384
	ds_read_b128 v[218:221], v173 offset:17408
	ds_read_b128 v[222:225], v173 offset:18432
	ds_read_b128 v[226:229], v173 offset:19456
	ds_read_b128 v[230:233], v173 offset:20480
	ds_read_b128 v[234:237], v173 offset:21504
	ds_read_b128 v[238:241], v173 offset:22528
	ds_read_b128 v[242:245], v173 offset:23552
	s_waitcnt vmcnt(8)
	s_waitcnt lgkmcnt(0)
	s_barrier
	s_setprio 1
	s_waitcnt lgkmcnt(0)
	v_mfma_f32_16x16x32_bf16 v[68:71], v[160:163], v[214:217], v[68:71]
	v_mfma_f32_16x16x32_bf16 v[64:67], v[174:177], v[214:217], v[64:67]
	v_mfma_f32_16x16x32_bf16 v[52:55], v[160:163], v[222:225], v[52:55]
	v_mfma_f32_16x16x32_bf16 v[48:51], v[174:177], v[222:225], v[48:51]
	v_mfma_f32_16x16x32_bf16 v[36:39], v[160:163], v[230:233], v[36:39]
	v_mfma_f32_16x16x32_bf16 v[30:33], v[174:177], v[230:233], v[30:33]
	v_mfma_f32_16x16x32_bf16 v[18:21], v[160:163], v[238:241], v[18:21]
	v_mfma_f32_16x16x32_bf16 v[10:13], v[174:177], v[238:241], v[10:13]
	v_mfma_f32_16x16x32_bf16 v[68:71], v[164:167], v[218:221], v[68:71]
	v_mfma_f32_16x16x32_bf16 v[64:67], v[184:187], v[218:221], v[64:67]
	v_mfma_f32_16x16x32_bf16 v[52:55], v[164:167], v[226:229], v[52:55]
	v_mfma_f32_16x16x32_bf16 v[48:51], v[184:187], v[226:229], v[48:51]
	v_mfma_f32_16x16x32_bf16 v[36:39], v[164:167], v[234:237], v[36:39]
	v_mfma_f32_16x16x32_bf16 v[30:33], v[184:187], v[234:237], v[30:33]
	v_mfma_f32_16x16x32_bf16 v[18:21], v[164:167], v[242:245], v[18:21]
	v_mfma_f32_16x16x32_bf16 v[10:13], v[184:187], v[242:245], v[10:13]
	s_setprio 0
	s_setprio 1
	v_mfma_f32_16x16x32_bf16 v[60:63], v[188:191], v[214:217], v[60:63]
	v_mfma_f32_16x16x32_bf16 v[56:59], v[196:199], v[214:217], v[56:59]
	v_mfma_f32_16x16x32_bf16 v[44:47], v[188:191], v[222:225], v[44:47]
	v_mfma_f32_16x16x32_bf16 v[40:43], v[196:199], v[222:225], v[40:43]
	v_mfma_f32_16x16x32_bf16 v[26:29], v[188:191], v[230:233], v[26:29]
	v_mfma_f32_16x16x32_bf16 v[22:25], v[196:199], v[230:233], v[22:25]
	v_mfma_f32_16x16x32_bf16 v[6:9], v[188:191], v[238:241], v[6:9]
	v_mfma_f32_16x16x32_bf16 v[2:5], v[196:199], v[238:241], v[2:5]
	v_mfma_f32_16x16x32_bf16 v[60:63], v[192:195], v[218:221], v[60:63]
	v_mfma_f32_16x16x32_bf16 v[56:59], v[200:203], v[218:221], v[56:59]
	v_mfma_f32_16x16x32_bf16 v[44:47], v[192:195], v[226:229], v[44:47]
	v_mfma_f32_16x16x32_bf16 v[40:43], v[200:203], v[226:229], v[40:43]
	v_mfma_f32_16x16x32_bf16 v[26:29], v[192:195], v[234:237], v[26:29]
	v_mfma_f32_16x16x32_bf16 v[22:25], v[200:203], v[234:237], v[22:25]
	v_mfma_f32_16x16x32_bf16 v[6:9], v[192:195], v[242:245], v[6:9]
	v_mfma_f32_16x16x32_bf16 v[2:5], v[200:203], v[242:245], v[2:5]
	s_setprio 0
	s_barrier
	s_add_i32 s45, 0, 0x18000
	v_add_u32_e32 v34, s45, v170
	s_add_i32 s47, 0, 0x1c000
	s_add_u32 s42, s42, 0x80000
	s_addc_u32 s43, s43, 0
	s_mov_b32 m0, s55
	global_load_lds_dwordx4 v14, s[42:43]
	s_mov_b32 m0, s60
	s_nop 0
	global_load_lds_dwordx4 v138, s[42:43]
	ds_read_b128 v[160:163], v34
	ds_read_b128 v[164:167], v34 offset:1024
	ds_read_b128 v[174:177], v34 offset:2048
	ds_read_b128 v[184:187], v34 offset:3072
	v_add_u32_e32 v34, s47, v170
	ds_read_b128 v[188:191], v34
	ds_read_b128 v[192:195], v34 offset:1024
	ds_read_b128 v[196:199], v34 offset:2048
	ds_read_b128 v[200:203], v34 offset:3072
	ds_read_b128 v[214:217], v173 offset:32768
	ds_read_b128 v[218:221], v173 offset:33792
	ds_read_b128 v[222:225], v173 offset:34816
	ds_read_b128 v[226:229], v173 offset:35840
	ds_read_b128 v[230:233], v173 offset:36864
	ds_read_b128 v[234:237], v173 offset:37888
	ds_read_b128 v[238:241], v173 offset:38912
	ds_read_b128 v[242:245], v173 offset:39936
	s_waitcnt vmcnt(8)
	s_waitcnt lgkmcnt(0)
	s_barrier
	s_setprio 1
	s_waitcnt lgkmcnt(0)
	v_mfma_f32_16x16x32_bf16 v[132:135], v[160:163], v[214:217], v[132:135]
	v_mfma_f32_16x16x32_bf16 v[128:131], v[174:177], v[214:217], v[128:131]
	v_mfma_f32_16x16x32_bf16 v[116:119], v[160:163], v[222:225], v[116:119]
	v_mfma_f32_16x16x32_bf16 v[112:115], v[174:177], v[222:225], v[112:115]
	v_mfma_f32_16x16x32_bf16 v[100:103], v[160:163], v[230:233], v[100:103]
	v_mfma_f32_16x16x32_bf16 v[96:99], v[174:177], v[230:233], v[96:99]
	v_mfma_f32_16x16x32_bf16 v[84:87], v[160:163], v[238:241], v[84:87]
	v_mfma_f32_16x16x32_bf16 v[80:83], v[174:177], v[238:241], v[80:83]
	v_mfma_f32_16x16x32_bf16 v[132:135], v[164:167], v[218:221], v[132:135]
	v_mfma_f32_16x16x32_bf16 v[128:131], v[184:187], v[218:221], v[128:131]
	v_mfma_f32_16x16x32_bf16 v[116:119], v[164:167], v[226:229], v[116:119]
	v_mfma_f32_16x16x32_bf16 v[112:115], v[184:187], v[226:229], v[112:115]
	v_mfma_f32_16x16x32_bf16 v[100:103], v[164:167], v[234:237], v[100:103]
	v_mfma_f32_16x16x32_bf16 v[96:99], v[184:187], v[234:237], v[96:99]
	v_mfma_f32_16x16x32_bf16 v[84:87], v[164:167], v[242:245], v[84:87]
	v_mfma_f32_16x16x32_bf16 v[80:83], v[184:187], v[242:245], v[80:83]
	s_setprio 0
	s_setprio 1
	v_mfma_f32_16x16x32_bf16 v[124:127], v[188:191], v[214:217], v[124:127]
	v_mfma_f32_16x16x32_bf16 v[120:123], v[196:199], v[214:217], v[120:123]
	v_mfma_f32_16x16x32_bf16 v[108:111], v[188:191], v[222:225], v[108:111]
	v_mfma_f32_16x16x32_bf16 v[104:107], v[196:199], v[222:225], v[104:107]
	v_mfma_f32_16x16x32_bf16 v[92:95], v[188:191], v[230:233], v[92:95]
	v_mfma_f32_16x16x32_bf16 v[88:91], v[196:199], v[230:233], v[88:91]
	v_mfma_f32_16x16x32_bf16 v[76:79], v[188:191], v[238:241], v[76:79]
	v_mfma_f32_16x16x32_bf16 v[72:75], v[196:199], v[238:241], v[72:75]
	v_mfma_f32_16x16x32_bf16 v[124:127], v[192:195], v[218:221], v[124:127]
	v_mfma_f32_16x16x32_bf16 v[120:123], v[200:203], v[218:221], v[120:123]
	v_mfma_f32_16x16x32_bf16 v[108:111], v[192:195], v[226:229], v[108:111]
	v_mfma_f32_16x16x32_bf16 v[104:107], v[200:203], v[226:229], v[104:107]
	v_mfma_f32_16x16x32_bf16 v[92:95], v[192:195], v[234:237], v[92:95]
	v_mfma_f32_16x16x32_bf16 v[88:91], v[200:203], v[234:237], v[88:91]
	v_mfma_f32_16x16x32_bf16 v[76:79], v[192:195], v[242:245], v[76:79]
	v_mfma_f32_16x16x32_bf16 v[72:75], v[200:203], v[242:245], v[72:75]
	s_setprio 0
	s_barrier
	s_add_i32 s42, s45, s53
	s_mov_b32 m0, s42
	global_load_lds_dwordx4 v136, s[98:99]
	s_add_i32 m0, s42, 0x2000
	s_add_u32 s38, s38, 0x80080
	s_addc_u32 s39, s39, 0
	s_add_i32 s42, s47, s53
	global_load_lds_dwordx4 v140, s[98:99]
	s_mov_b32 m0, s42
	s_nop 0
	global_load_lds_dwordx4 v136, s[38:39]
	s_add_i32 m0, s42, 0x2000
	s_nop 0
	global_load_lds_dwordx4 v140, s[38:39]
	s_mov_b32 m0, s61
	s_nop 0
	global_load_lds_dwordx4 v14, s[100:101]
	s_mov_b32 m0, s64
	s_nop 0
	global_load_lds_dwordx4 v138, s[100:101]
	ds_read_b128 v[214:217], v173 offset:49152
	ds_read_b128 v[218:221], v173 offset:50176
	ds_read_b128 v[222:225], v173 offset:51200
	ds_read_b128 v[226:229], v173 offset:52224
	ds_read_b128 v[230:233], v173 offset:53248
	ds_read_b128 v[234:237], v173 offset:54272
	ds_read_b128 v[238:241], v173 offset:55296
	ds_read_b128 v[242:245], v173 offset:56320
	s_waitcnt vmcnt(8)
	s_waitcnt lgkmcnt(0)
	s_barrier
	s_setprio 1
	s_waitcnt lgkmcnt(0)
	v_mfma_f32_16x16x32_bf16 v[68:71], v[160:163], v[214:217], v[68:71]
	v_mfma_f32_16x16x32_bf16 v[64:67], v[174:177], v[214:217], v[64:67]
	v_mfma_f32_16x16x32_bf16 v[52:55], v[160:163], v[222:225], v[52:55]
	v_mfma_f32_16x16x32_bf16 v[48:51], v[174:177], v[222:225], v[48:51]
	v_mfma_f32_16x16x32_bf16 v[36:39], v[160:163], v[230:233], v[36:39]
	v_mfma_f32_16x16x32_bf16 v[30:33], v[174:177], v[230:233], v[30:33]
	v_mfma_f32_16x16x32_bf16 v[18:21], v[160:163], v[238:241], v[18:21]
	v_mfma_f32_16x16x32_bf16 v[10:13], v[174:177], v[238:241], v[10:13]
	v_mfma_f32_16x16x32_bf16 v[68:71], v[164:167], v[218:221], v[68:71]
	v_mfma_f32_16x16x32_bf16 v[64:67], v[184:187], v[218:221], v[64:67]
	v_mfma_f32_16x16x32_bf16 v[52:55], v[164:167], v[226:229], v[52:55]
	v_mfma_f32_16x16x32_bf16 v[48:51], v[184:187], v[226:229], v[48:51]
	v_mfma_f32_16x16x32_bf16 v[36:39], v[164:167], v[234:237], v[36:39]
	v_mfma_f32_16x16x32_bf16 v[30:33], v[184:187], v[234:237], v[30:33]
	v_mfma_f32_16x16x32_bf16 v[18:21], v[164:167], v[242:245], v[18:21]
	v_mfma_f32_16x16x32_bf16 v[10:13], v[184:187], v[242:245], v[10:13]
	s_setprio 0
	s_setprio 1
	v_mfma_f32_16x16x32_bf16 v[60:63], v[188:191], v[214:217], v[60:63]
	v_mfma_f32_16x16x32_bf16 v[56:59], v[196:199], v[214:217], v[56:59]
	v_mfma_f32_16x16x32_bf16 v[44:47], v[188:191], v[222:225], v[44:47]
	v_mfma_f32_16x16x32_bf16 v[40:43], v[196:199], v[222:225], v[40:43]
	v_mfma_f32_16x16x32_bf16 v[26:29], v[188:191], v[230:233], v[26:29]
	v_mfma_f32_16x16x32_bf16 v[22:25], v[196:199], v[230:233], v[22:25]
	v_mfma_f32_16x16x32_bf16 v[6:9], v[188:191], v[238:241], v[6:9]
	v_mfma_f32_16x16x32_bf16 v[2:5], v[196:199], v[238:241], v[2:5]
	v_mfma_f32_16x16x32_bf16 v[60:63], v[192:195], v[218:221], v[60:63]
	v_mfma_f32_16x16x32_bf16 v[56:59], v[200:203], v[218:221], v[56:59]
	v_mfma_f32_16x16x32_bf16 v[44:47], v[192:195], v[226:229], v[44:47]
	v_mfma_f32_16x16x32_bf16 v[40:43], v[200:203], v[226:229], v[40:43]
	v_mfma_f32_16x16x32_bf16 v[26:29], v[192:195], v[234:237], v[26:29]
	v_mfma_f32_16x16x32_bf16 v[22:25], v[200:203], v[234:237], v[22:25]
	v_mfma_f32_16x16x32_bf16 v[6:9], v[192:195], v[242:245], v[6:9]
	v_mfma_f32_16x16x32_bf16 v[2:5], v[200:203], v[242:245], v[2:5]
	s_setprio 0
	s_barrier
	s_add_i32 s27, s27, 2
	s_add_u32 s36, s36, 0x100
	s_addc_u32 s37, s37, 0
	s_add_u32 s25, s25, 0x100
	s_addc_u32 s26, s26, 0
	s_cmp_gt_u32 s27, 29
	s_cbranch_scc0 .LBB0_306
	s_and_b64 vcc, exec, s[28:29]
	s_cbranch_vccz .LBB0_309
	s_barrier

.LBB0_1124:
	s_add_i32 vcc_lo, s44, 2
	s_add_u32 s38, s8, 0x100
	s_addc_u32 s39, s9, 0
	s_add_i32 s72, 0, 0x10000
	s_cmp_eq_u32 s29, s44
	s_cselect_b32 s47, s35, s39
	s_cselect_b32 s46, s34, s38
	v_add_u32_e32 v34, s72, v183
	s_cselect_b32 s45, s49, s71
	s_cselect_b32 s44, s48, s70
	s_add_i32 s73, 0, 0x14000
	s_add_i32 m0, s25, 0xc000
	global_load_lds_dwordx4 v192, s[8:9]
	s_add_i32 m0, s25, 0xe000
	s_nop 0
	global_load_lds_dwordx4 v194, s[8:9]
	ds_read_b128 v[42:45], v34
	ds_read_b128 v[46:49], v34 offset:1024
	ds_read_b128 v[74:77], v34 offset:2048
	ds_read_b128 v[78:81], v34 offset:3072
	v_add_u32_e32 v34, s73, v183
	ds_read_b128 v[106:109], v34
	ds_read_b128 v[110:113], v34 offset:1024
	ds_read_b128 v[138:141], v34 offset:2048
	ds_read_b128 v[142:145], v34 offset:3072
	ds_read_b128 v[170:173], v205
	ds_read_b128 v[174:177], v205 offset:1024
	ds_read_b128 v[196:199], v205 offset:2048
	ds_read_b128 v[200:203], v205 offset:3072
	ds_read_b128 v[214:217], v205 offset:4096
	ds_read_b128 v[218:221], v205 offset:5120
	ds_read_b128 v[222:225], v205 offset:6144
	ds_read_b128 v[226:229], v205 offset:7168
	s_waitcnt vmcnt(8)
	s_waitcnt lgkmcnt(0)
	s_barrier
	s_setprio 1
	s_waitcnt lgkmcnt(0)
	v_mfma_f32_16x16x32_bf16 v[62:65], v[42:45], v[170:173], v[62:65]
	v_mfma_f32_16x16x32_bf16 v[58:61], v[74:77], v[170:173], v[58:61]
	v_mfma_f32_16x16x32_bf16 v[94:97], v[42:45], v[196:199], v[94:97]
	v_mfma_f32_16x16x32_bf16 v[90:93], v[74:77], v[196:199], v[90:93]
	v_mfma_f32_16x16x32_bf16 v[118:121], v[42:45], v[214:217], v[118:121]
	v_mfma_f32_16x16x32_bf16 v[114:117], v[74:77], v[214:217], v[114:117]
	v_mfma_f32_16x16x32_bf16 v[134:137], v[42:45], v[222:225], v[134:137]
	v_mfma_f32_16x16x32_bf16 v[130:133], v[74:77], v[222:225], v[130:133]
	v_mfma_f32_16x16x32_bf16 v[62:65], v[46:49], v[174:177], v[62:65]
	v_mfma_f32_16x16x32_bf16 v[58:61], v[78:81], v[174:177], v[58:61]
	v_mfma_f32_16x16x32_bf16 v[94:97], v[46:49], v[200:203], v[94:97]
	v_mfma_f32_16x16x32_bf16 v[90:93], v[78:81], v[200:203], v[90:93]
	v_mfma_f32_16x16x32_bf16 v[118:121], v[46:49], v[218:221], v[118:121]
	v_mfma_f32_16x16x32_bf16 v[114:117], v[78:81], v[218:221], v[114:117]
	v_mfma_f32_16x16x32_bf16 v[134:137], v[46:49], v[226:229], v[134:137]
	v_mfma_f32_16x16x32_bf16 v[130:133], v[78:81], v[226:229], v[130:133]
	s_setprio 0
	s_setprio 1
	v_mfma_f32_16x16x32_bf16 v[166:169], v[106:109], v[170:173], v[166:169]
	v_mfma_f32_16x16x32_bf16 v[162:165], v[138:141], v[170:173], v[162:165]
	v_mfma_f32_16x16x32_bf16 v[158:161], v[106:109], v[196:199], v[158:161]
	v_mfma_f32_16x16x32_bf16 v[154:157], v[138:141], v[196:199], v[154:157]
	v_mfma_f32_16x16x32_bf16 v[150:153], v[106:109], v[214:217], v[150:153]
	v_mfma_f32_16x16x32_bf16 v[146:149], v[138:141], v[214:217], v[146:149]
	v_mfma_f32_16x16x32_bf16 v[126:129], v[106:109], v[222:225], v[126:129]
	v_mfma_f32_16x16x32_bf16 v[122:125], v[138:141], v[222:225], v[122:125]
	v_mfma_f32_16x16x32_bf16 v[166:169], v[110:113], v[174:177], v[166:169]
	v_mfma_f32_16x16x32_bf16 v[162:165], v[142:145], v[174:177], v[162:165]
	v_mfma_f32_16x16x32_bf16 v[158:161], v[110:113], v[200:203], v[158:161]
	v_mfma_f32_16x16x32_bf16 v[154:157], v[142:145], v[200:203], v[154:157]
	v_mfma_f32_16x16x32_bf16 v[150:153], v[110:113], v[218:221], v[150:153]
	v_mfma_f32_16x16x32_bf16 v[146:149], v[142:145], v[218:221], v[146:149]
	v_mfma_f32_16x16x32_bf16 v[126:129], v[110:113], v[226:229], v[126:129]
	v_mfma_f32_16x16x32_bf16 v[122:125], v[142:145], v[226:229], v[122:125]
	s_setprio 0
	s_barrier
	s_add_u32 s98, s44, s22
	s_addc_u32 s99, s45, s23
	s_add_u32 s100, s46, s22
	s_addc_u32 s101, s47, s23
	s_add_i32 s8, s72, s20
	s_mov_b32 m0, s8
	global_load_lds_dwordx4 v184, s[44:45]
	s_add_i32 m0, s8, 0x2000
	s_add_u32 s8, s44, 0xc0000
	s_addc_u32 s9, s45, 0
	s_add_i32 s72, s73, s20
	global_load_lds_dwordx4 v188, s[44:45]
	s_mov_b32 m0, s72
	global_load_lds_dwordx4 v184, s[8:9]
	s_add_i32 m0, s72, 0x2000
	global_load_lds_dwordx4 v188, s[8:9]
	s_mov_b32 m0, s25
	s_nop 0
	global_load_lds_dwordx4 v14, s[46:47]
	s_mov_b32 m0, s26
	s_nop 0
	global_load_lds_dwordx4 v186, s[46:47]
	ds_read_b128 v[170:173], v205 offset:16384
	ds_read_b128 v[174:177], v205 offset:17408
	ds_read_b128 v[196:199], v205 offset:18432
	ds_read_b128 v[200:203], v205 offset:19456
	ds_read_b128 v[214:217], v205 offset:20480
	ds_read_b128 v[218:221], v205 offset:21504
	ds_read_b128 v[222:225], v205 offset:22528
	ds_read_b128 v[226:229], v205 offset:23552
	s_waitcnt vmcnt(8)
	s_waitcnt lgkmcnt(0)
	s_barrier
	s_setprio 1
	s_waitcnt lgkmcnt(0)
	v_mfma_f32_16x16x32_bf16 v[102:105], v[42:45], v[170:173], v[102:105]
	v_mfma_f32_16x16x32_bf16 v[98:101], v[74:77], v[170:173], v[98:101]
	v_mfma_f32_16x16x32_bf16 v[70:73], v[42:45], v[196:199], v[70:73]
	v_mfma_f32_16x16x32_bf16 v[66:69], v[74:77], v[196:199], v[66:69]
	v_mfma_f32_16x16x32_bf16 v[36:39], v[42:45], v[214:217], v[38:41]
	v_mfma_f32_16x16x32_bf16 v[30:33], v[74:77], v[214:217], v[30:33]
	v_mfma_f32_16x16x32_bf16 v[18:21], v[42:45], v[222:225], v[18:21]
	v_mfma_f32_16x16x32_bf16 v[10:13], v[74:77], v[222:225], v[10:13]
	v_mfma_f32_16x16x32_bf16 v[102:105], v[46:49], v[174:177], v[102:105]
	v_mfma_f32_16x16x32_bf16 v[98:101], v[78:81], v[174:177], v[98:101]
	v_mfma_f32_16x16x32_bf16 v[70:73], v[46:49], v[200:203], v[70:73]
	v_mfma_f32_16x16x32_bf16 v[66:69], v[78:81], v[200:203], v[66:69]
	v_mfma_f32_16x16x32_bf16 v[36:39], v[46:49], v[218:221], v[36:39]
	v_mfma_f32_16x16x32_bf16 v[30:33], v[78:81], v[218:221], v[30:33]
	v_mfma_f32_16x16x32_bf16 v[18:21], v[46:49], v[226:229], v[18:21]
	v_mfma_f32_16x16x32_bf16 v[10:13], v[78:81], v[226:229], v[10:13]
	s_setprio 0
	s_setprio 1
	v_mfma_f32_16x16x32_bf16 v[54:57], v[106:109], v[196:199], v[54:57]
	v_mfma_f32_16x16x32_bf16 v[50:53], v[138:141], v[196:199], v[50:53]
	v_mfma_f32_16x16x32_bf16 v[26:29], v[106:109], v[214:217], v[26:29]
	v_mfma_f32_16x16x32_bf16 v[22:25], v[138:141], v[214:217], v[22:25]
	v_mfma_f32_16x16x32_bf16 v[6:9], v[106:109], v[222:225], v[6:9]
	v_mfma_f32_16x16x32_bf16 v[2:5], v[138:141], v[222:225], v[2:5]
	v_mfma_f32_16x16x32_bf16 v[40:43], v[106:109], v[170:173], v[86:89]
	v_mfma_f32_16x16x32_bf16 v[46:49], v[138:141], v[170:173], v[82:85]
	v_mfma_f32_16x16x32_bf16 v[54:57], v[110:113], v[200:203], v[54:57]
	v_mfma_f32_16x16x32_bf16 v[50:53], v[142:145], v[200:203], v[50:53]
	v_mfma_f32_16x16x32_bf16 v[26:29], v[110:113], v[218:221], v[26:29]
	v_mfma_f32_16x16x32_bf16 v[22:25], v[142:145], v[218:221], v[22:25]
	v_mfma_f32_16x16x32_bf16 v[6:9], v[110:113], v[226:229], v[6:9]
	v_mfma_f32_16x16x32_bf16 v[2:5], v[142:145], v[226:229], v[2:5]
	v_mfma_f32_16x16x32_bf16 v[42:45], v[110:113], v[174:177], v[40:43]
	v_mfma_f32_16x16x32_bf16 v[46:49], v[142:145], v[174:177], v[46:49]
	s_setprio 0
	s_barrier
	s_add_i32 s72, 0, 0x18000
	v_add_u32_e32 v34, s72, v183
	s_add_i32 s73, 0, 0x1c000
	s_add_u32 s8, s46, 0xc0000
	s_addc_u32 s9, s47, 0
	s_mov_b32 m0, s27
	global_load_lds_dwordx4 v14, s[8:9]
	s_mov_b32 m0, s31
	s_nop 0
	global_load_lds_dwordx4 v186, s[8:9]
	ds_read_b128 v[74:77], v34
	ds_read_b128 v[78:81], v34 offset:1024
	ds_read_b128 v[82:85], v34 offset:2048
	ds_read_b128 v[86:89], v34 offset:3072
	v_add_u32_e32 v34, s73, v183
	ds_read_b128 v[106:109], v34
	ds_read_b128 v[110:113], v34 offset:1024
	ds_read_b128 v[138:141], v34 offset:2048
	ds_read_b128 v[142:145], v34 offset:3072
	ds_read_b128 v[170:173], v205 offset:32768
	ds_read_b128 v[174:177], v205 offset:33792
	ds_read_b128 v[196:199], v205 offset:34816
	ds_read_b128 v[200:203], v205 offset:35840
	ds_read_b128 v[214:217], v205 offset:36864
	ds_read_b128 v[218:221], v205 offset:37888
	ds_read_b128 v[222:225], v205 offset:38912
	ds_read_b128 v[226:229], v205 offset:39936
	s_waitcnt vmcnt(8)
	s_waitcnt lgkmcnt(0)
	s_barrier
	s_setprio 1
	s_waitcnt lgkmcnt(0)
	v_mfma_f32_16x16x32_bf16 v[62:65], v[74:77], v[170:173], v[62:65]
	v_mfma_f32_16x16x32_bf16 v[58:61], v[82:85], v[170:173], v[58:61]
	v_mfma_f32_16x16x32_bf16 v[94:97], v[74:77], v[196:199], v[94:97]
	v_mfma_f32_16x16x32_bf16 v[90:93], v[82:85], v[196:199], v[90:93]
	v_mfma_f32_16x16x32_bf16 v[118:121], v[74:77], v[214:217], v[118:121]
	v_mfma_f32_16x16x32_bf16 v[114:117], v[82:85], v[214:217], v[114:117]
	v_mfma_f32_16x16x32_bf16 v[134:137], v[74:77], v[222:225], v[134:137]
	v_mfma_f32_16x16x32_bf16 v[130:133], v[82:85], v[222:225], v[130:133]
	v_mfma_f32_16x16x32_bf16 v[62:65], v[78:81], v[174:177], v[62:65]
	v_mfma_f32_16x16x32_bf16 v[58:61], v[86:89], v[174:177], v[58:61]
	v_mfma_f32_16x16x32_bf16 v[94:97], v[78:81], v[200:203], v[94:97]
	v_mfma_f32_16x16x32_bf16 v[90:93], v[86:89], v[200:203], v[90:93]
	v_mfma_f32_16x16x32_bf16 v[118:121], v[78:81], v[218:221], v[118:121]
	v_mfma_f32_16x16x32_bf16 v[114:117], v[86:89], v[218:221], v[114:117]
	v_mfma_f32_16x16x32_bf16 v[134:137], v[78:81], v[226:229], v[134:137]
	v_mfma_f32_16x16x32_bf16 v[130:133], v[86:89], v[226:229], v[130:133]
	s_setprio 0
	s_setprio 1
	v_mfma_f32_16x16x32_bf16 v[166:169], v[106:109], v[170:173], v[166:169]
	v_mfma_f32_16x16x32_bf16 v[162:165], v[138:141], v[170:173], v[162:165]
	v_mfma_f32_16x16x32_bf16 v[158:161], v[106:109], v[196:199], v[158:161]
	v_mfma_f32_16x16x32_bf16 v[154:157], v[138:141], v[196:199], v[154:157]
	v_mfma_f32_16x16x32_bf16 v[150:153], v[106:109], v[214:217], v[150:153]
	v_mfma_f32_16x16x32_bf16 v[146:149], v[138:141], v[214:217], v[146:149]
	v_mfma_f32_16x16x32_bf16 v[126:129], v[106:109], v[222:225], v[126:129]
	v_mfma_f32_16x16x32_bf16 v[122:125], v[138:141], v[222:225], v[122:125]
	v_mfma_f32_16x16x32_bf16 v[166:169], v[110:113], v[174:177], v[166:169]
	v_mfma_f32_16x16x32_bf16 v[162:165], v[142:145], v[174:177], v[162:165]
	v_mfma_f32_16x16x32_bf16 v[158:161], v[110:113], v[200:203], v[158:161]
	v_mfma_f32_16x16x32_bf16 v[154:157], v[142:145], v[200:203], v[154:157]
	v_mfma_f32_16x16x32_bf16 v[150:153], v[110:113], v[218:221], v[150:153]
	v_mfma_f32_16x16x32_bf16 v[146:149], v[142:145], v[218:221], v[146:149]
	v_mfma_f32_16x16x32_bf16 v[126:129], v[110:113], v[226:229], v[126:129]
	v_mfma_f32_16x16x32_bf16 v[122:125], v[142:145], v[226:229], v[122:125]
	s_setprio 0
	s_barrier
	s_add_i32 s8, s72, s20
	s_mov_b32 m0, s8
	global_load_lds_dwordx4 v184, s[98:99]
	s_add_i32 m0, s8, 0x2000
	s_add_u32 s8, s44, 0xc0080
	s_addc_u32 s9, s45, 0
	s_add_i32 s44, s73, s20
	global_load_lds_dwordx4 v188, s[98:99]
	s_mov_b32 m0, s44
	s_nop 0
	global_load_lds_dwordx4 v184, s[8:9]
	s_add_i32 m0, s44, 0x2000
	s_nop 0
	global_load_lds_dwordx4 v188, s[8:9]
	s_mov_b32 m0, s52
	s_nop 0
	global_load_lds_dwordx4 v14, s[100:101]
	s_mov_b32 m0, s53
	s_nop 0
	global_load_lds_dwordx4 v186, s[100:101]
	ds_read_b128 v[170:173], v205 offset:49152
	ds_read_b128 v[174:177], v205 offset:50176
	ds_read_b128 v[196:199], v205 offset:51200
	ds_read_b128 v[200:203], v205 offset:52224
	ds_read_b128 v[214:217], v205 offset:53248
	ds_read_b128 v[218:221], v205 offset:54272
	ds_read_b128 v[222:225], v205 offset:55296
	ds_read_b128 v[226:229], v205 offset:56320
	s_waitcnt vmcnt(8)
	s_waitcnt lgkmcnt(0)
	s_barrier
	s_setprio 1
	s_waitcnt lgkmcnt(0)
	v_mfma_f32_16x16x32_bf16 v[102:105], v[74:77], v[170:173], v[102:105]
	v_mfma_f32_16x16x32_bf16 v[98:101], v[82:85], v[170:173], v[98:101]
	v_mfma_f32_16x16x32_bf16 v[70:73], v[74:77], v[196:199], v[70:73]
	v_mfma_f32_16x16x32_bf16 v[66:69], v[82:85], v[196:199], v[66:69]
	v_mfma_f32_16x16x32_bf16 v[36:39], v[74:77], v[214:217], v[36:39]
	v_mfma_f32_16x16x32_bf16 v[30:33], v[82:85], v[214:217], v[30:33]
	v_mfma_f32_16x16x32_bf16 v[18:21], v[74:77], v[222:225], v[18:21]
	v_mfma_f32_16x16x32_bf16 v[10:13], v[82:85], v[222:225], v[10:13]
	v_mfma_f32_16x16x32_bf16 v[102:105], v[78:81], v[174:177], v[102:105]
	v_mfma_f32_16x16x32_bf16 v[98:101], v[86:89], v[174:177], v[98:101]
	v_mfma_f32_16x16x32_bf16 v[70:73], v[78:81], v[200:203], v[70:73]
	v_mfma_f32_16x16x32_bf16 v[66:69], v[86:89], v[200:203], v[66:69]
	v_mfma_f32_16x16x32_bf16 v[38:41], v[78:81], v[218:221], v[36:39]
	v_mfma_f32_16x16x32_bf16 v[30:33], v[86:89], v[218:221], v[30:33]
	v_mfma_f32_16x16x32_bf16 v[18:21], v[78:81], v[226:229], v[18:21]
	v_mfma_f32_16x16x32_bf16 v[10:13], v[86:89], v[226:229], v[10:13]
	s_setprio 0
	s_setprio 1
	v_mfma_f32_16x16x32_bf16 v[42:45], v[106:109], v[170:173], v[42:45]
	v_mfma_f32_16x16x32_bf16 v[86:89], v[110:113], v[174:177], v[42:45]
	v_mfma_f32_16x16x32_bf16 v[42:45], v[138:141], v[170:173], v[46:49]
	v_mfma_f32_16x16x32_bf16 v[82:85], v[142:145], v[174:177], v[42:45]
	v_mfma_f32_16x16x32_bf16 v[42:45], v[106:109], v[196:199], v[54:57]
	v_mfma_f32_16x16x32_bf16 v[54:57], v[110:113], v[200:203], v[42:45]
	v_mfma_f32_16x16x32_bf16 v[42:45], v[138:141], v[196:199], v[50:53]
	v_mfma_f32_16x16x32_bf16 v[26:29], v[106:109], v[214:217], v[26:29]
	v_mfma_f32_16x16x32_bf16 v[22:25], v[138:141], v[214:217], v[22:25]
	v_mfma_f32_16x16x32_bf16 v[6:9], v[106:109], v[222:225], v[6:9]
	v_mfma_f32_16x16x32_bf16 v[2:5], v[138:141], v[222:225], v[2:5]
	v_mfma_f32_16x16x32_bf16 v[50:53], v[142:145], v[200:203], v[42:45]
	v_mfma_f32_16x16x32_bf16 v[26:29], v[110:113], v[218:221], v[26:29]
	v_mfma_f32_16x16x32_bf16 v[22:25], v[142:145], v[218:221], v[22:25]
	v_mfma_f32_16x16x32_bf16 v[6:9], v[110:113], v[226:229], v[6:9]
	v_mfma_f32_16x16x32_bf16 v[2:5], v[142:145], v[226:229], v[2:5]
	s_setprio 0
	s_barrier
	s_add_u32 s70, s70, 0x100
	s_addc_u32 s71, s71, 0
	s_cmp_ge_i32 vcc_lo, s51
	s_mov_b64 s[8:9], s[38:39]
	s_mov_b32 s44, vcc_lo
	s_cbranch_scc0 .LBB0_1124
	s_and_b64 vcc, exec, s[12:13]
	s_cbranch_vccz .LBB0_1127
	s_barrier

.LBB0_1508:
	s_add_i32 s39, s35, 2
	s_add_u32 s50, s48, 0xfff80080
	s_addc_u32 s51, s49, -1
	s_add_i32 s72, 0, 0x10000
	s_cmp_eq_u32 s9, s35
	s_cselect_b32 s53, s37, s51
	s_cselect_b32 s52, s36, s50
	s_cselect_b32 s51, s45, s29
	s_cselect_b32 s50, s44, s13
	s_add_i32 s35, 0, 0x14000
	v_add_u32_e32 v160, s72, v152
	v_add_u32_e32 v176, s35, v152
	s_add_i32 m0, s25, 0xc000
	global_load_lds_dwordx4 v144, s[48:49]
	s_add_i32 m0, s25, 0xe000
	s_nop 0
	global_load_lds_dwordx4 v146, s[48:49]
	ds_read_b128 v[136:139], v160
	ds_read_b128 v[148:151], v160 offset:1024
	ds_read_b128 v[156:159], v160 offset:2048
	ds_read_b128 v[160:163], v160 offset:3072
	ds_read_b128 v[164:167], v176
	ds_read_b128 v[168:171], v176 offset:1024
	ds_read_b128 v[172:175], v176 offset:2048
	ds_read_b128 v[184:187], v176 offset:3072
	ds_read_b128 v[188:191], v155
	ds_read_b128 v[192:195], v155 offset:1024
	ds_read_b128 v[196:199], v155 offset:2048
	ds_read_b128 v[200:203], v155 offset:3072
	ds_read_b128 v[214:217], v155 offset:4096
	ds_read_b128 v[218:221], v155 offset:5120
	ds_read_b128 v[222:225], v155 offset:6144
	ds_read_b128 v[226:229], v155 offset:7168
	s_waitcnt vmcnt(8)
	s_waitcnt lgkmcnt(0)
	s_barrier
	s_setprio 1
	s_waitcnt lgkmcnt(0)
	v_mfma_f32_16x16x32_bf16 v[132:135], v[136:139], v[188:191], v[132:135]
	v_mfma_f32_16x16x32_bf16 v[128:131], v[156:159], v[188:191], v[128:131]
	v_mfma_f32_16x16x32_bf16 v[116:119], v[136:139], v[196:199], v[116:119]
	v_mfma_f32_16x16x32_bf16 v[112:115], v[156:159], v[196:199], v[112:115]
	v_mfma_f32_16x16x32_bf16 v[100:103], v[136:139], v[214:217], v[100:103]
	v_mfma_f32_16x16x32_bf16 v[96:99], v[156:159], v[214:217], v[96:99]
	v_mfma_f32_16x16x32_bf16 v[84:87], v[136:139], v[222:225], v[84:87]
	v_mfma_f32_16x16x32_bf16 v[80:83], v[156:159], v[222:225], v[80:83]
	v_mfma_f32_16x16x32_bf16 v[132:135], v[148:151], v[192:195], v[132:135]
	v_mfma_f32_16x16x32_bf16 v[128:131], v[160:163], v[192:195], v[128:131]
	v_mfma_f32_16x16x32_bf16 v[116:119], v[148:151], v[200:203], v[116:119]
	v_mfma_f32_16x16x32_bf16 v[112:115], v[160:163], v[200:203], v[112:115]
	v_mfma_f32_16x16x32_bf16 v[100:103], v[148:151], v[218:221], v[100:103]
	v_mfma_f32_16x16x32_bf16 v[96:99], v[160:163], v[218:221], v[96:99]
	v_mfma_f32_16x16x32_bf16 v[84:87], v[148:151], v[226:229], v[84:87]
	v_mfma_f32_16x16x32_bf16 v[80:83], v[160:163], v[226:229], v[80:83]
	s_setprio 0
	s_setprio 1
	v_mfma_f32_16x16x32_bf16 v[124:127], v[164:167], v[188:191], v[124:127]
	v_mfma_f32_16x16x32_bf16 v[120:123], v[172:175], v[188:191], v[120:123]
	v_mfma_f32_16x16x32_bf16 v[108:111], v[164:167], v[196:199], v[108:111]
	v_mfma_f32_16x16x32_bf16 v[104:107], v[172:175], v[196:199], v[104:107]
	v_mfma_f32_16x16x32_bf16 v[92:95], v[164:167], v[214:217], v[92:95]
	v_mfma_f32_16x16x32_bf16 v[88:91], v[172:175], v[214:217], v[88:91]
	v_mfma_f32_16x16x32_bf16 v[76:79], v[164:167], v[222:225], v[76:79]
	v_mfma_f32_16x16x32_bf16 v[72:75], v[172:175], v[222:225], v[72:75]
	v_mfma_f32_16x16x32_bf16 v[124:127], v[168:171], v[192:195], v[124:127]
	v_mfma_f32_16x16x32_bf16 v[120:123], v[184:187], v[192:195], v[120:123]
	v_mfma_f32_16x16x32_bf16 v[108:111], v[168:171], v[200:203], v[108:111]
	v_mfma_f32_16x16x32_bf16 v[104:107], v[184:187], v[200:203], v[104:107]
	v_mfma_f32_16x16x32_bf16 v[92:95], v[168:171], v[218:221], v[92:95]
	v_mfma_f32_16x16x32_bf16 v[88:91], v[184:187], v[218:221], v[88:91]
	v_mfma_f32_16x16x32_bf16 v[76:79], v[168:171], v[226:229], v[76:79]
	v_mfma_f32_16x16x32_bf16 v[72:75], v[184:187], v[226:229], v[72:75]
	s_setprio 0
	s_barrier
	s_add_u32 s98, s50, s22
	s_addc_u32 s99, s51, s23
	s_add_u32 s100, s52, s22
	s_addc_u32 s101, s53, s23
	s_add_i32 s72, s72, s20
	s_mov_b32 m0, s72
	global_load_lds_dwordx4 v34, s[50:51]
	s_add_i32 m0, s72, 0x2000
	s_add_u32 s72, s50, 0x80000
	s_addc_u32 s73, s51, 0
	s_add_i32 s35, s35, s20
	global_load_lds_dwordx4 v142, s[50:51]
	s_mov_b32 m0, s35
	global_load_lds_dwordx4 v34, s[72:73]
	s_add_i32 m0, s35, 0x2000
	s_nop 0
	global_load_lds_dwordx4 v142, s[72:73]
	s_mov_b32 m0, s25
	s_nop 0
	global_load_lds_dwordx4 v14, s[52:53]
	s_mov_b32 m0, s26
	s_nop 0
	global_load_lds_dwordx4 v140, s[52:53]
	ds_read_b128 v[188:191], v155 offset:16384
	ds_read_b128 v[192:195], v155 offset:17408
	ds_read_b128 v[196:199], v155 offset:18432
	ds_read_b128 v[200:203], v155 offset:19456
	ds_read_b128 v[214:217], v155 offset:20480
	ds_read_b128 v[218:221], v155 offset:21504
	ds_read_b128 v[222:225], v155 offset:22528
	ds_read_b128 v[226:229], v155 offset:23552
	s_waitcnt vmcnt(8)
	s_waitcnt lgkmcnt(0)
	s_barrier
	s_setprio 1
	s_waitcnt lgkmcnt(0)
	v_mfma_f32_16x16x32_bf16 v[68:71], v[136:139], v[188:191], v[68:71]
	v_mfma_f32_16x16x32_bf16 v[64:67], v[156:159], v[188:191], v[64:67]
	v_mfma_f32_16x16x32_bf16 v[52:55], v[136:139], v[196:199], v[52:55]
	v_mfma_f32_16x16x32_bf16 v[48:51], v[156:159], v[196:199], v[48:51]
	v_mfma_f32_16x16x32_bf16 v[36:39], v[136:139], v[214:217], v[36:39]
	v_mfma_f32_16x16x32_bf16 v[30:33], v[156:159], v[214:217], v[30:33]
	v_mfma_f32_16x16x32_bf16 v[18:21], v[136:139], v[222:225], v[18:21]
	v_mfma_f32_16x16x32_bf16 v[10:13], v[156:159], v[222:225], v[10:13]
	v_mfma_f32_16x16x32_bf16 v[68:71], v[148:151], v[192:195], v[68:71]
	v_mfma_f32_16x16x32_bf16 v[64:67], v[160:163], v[192:195], v[64:67]
	v_mfma_f32_16x16x32_bf16 v[52:55], v[148:151], v[200:203], v[52:55]
	v_mfma_f32_16x16x32_bf16 v[48:51], v[160:163], v[200:203], v[48:51]
	v_mfma_f32_16x16x32_bf16 v[36:39], v[148:151], v[218:221], v[36:39]
	v_mfma_f32_16x16x32_bf16 v[30:33], v[160:163], v[218:221], v[30:33]
	v_mfma_f32_16x16x32_bf16 v[18:21], v[148:151], v[226:229], v[18:21]
	v_mfma_f32_16x16x32_bf16 v[10:13], v[160:163], v[226:229], v[10:13]
	s_setprio 0
	s_setprio 1
	v_mfma_f32_16x16x32_bf16 v[60:63], v[164:167], v[188:191], v[60:63]
	v_mfma_f32_16x16x32_bf16 v[56:59], v[172:175], v[188:191], v[56:59]
	v_mfma_f32_16x16x32_bf16 v[44:47], v[164:167], v[196:199], v[44:47]
	v_mfma_f32_16x16x32_bf16 v[40:43], v[172:175], v[196:199], v[40:43]
	v_mfma_f32_16x16x32_bf16 v[26:29], v[164:167], v[214:217], v[26:29]
	v_mfma_f32_16x16x32_bf16 v[22:25], v[172:175], v[214:217], v[22:25]
	v_mfma_f32_16x16x32_bf16 v[6:9], v[164:167], v[222:225], v[6:9]
	v_mfma_f32_16x16x32_bf16 v[2:5], v[172:175], v[222:225], v[2:5]
	v_mfma_f32_16x16x32_bf16 v[60:63], v[168:171], v[192:195], v[60:63]
	v_mfma_f32_16x16x32_bf16 v[56:59], v[184:187], v[192:195], v[56:59]
	v_mfma_f32_16x16x32_bf16 v[44:47], v[168:171], v[200:203], v[44:47]
	v_mfma_f32_16x16x32_bf16 v[40:43], v[184:187], v[200:203], v[40:43]
	v_mfma_f32_16x16x32_bf16 v[26:29], v[168:171], v[218:221], v[26:29]
	v_mfma_f32_16x16x32_bf16 v[22:25], v[184:187], v[218:221], v[22:25]
	v_mfma_f32_16x16x32_bf16 v[6:9], v[168:171], v[226:229], v[6:9]
	v_mfma_f32_16x16x32_bf16 v[2:5], v[184:187], v[226:229], v[2:5]
	s_setprio 0
	s_barrier
	s_add_i32 s35, 0, 0x18000
	s_add_i32 s72, 0, 0x1c000
	v_add_u32_e32 v160, s35, v152
	v_add_u32_e32 v183, s72, v152
	s_add_u32 s52, s52, 0x80000
	s_addc_u32 s53, s53, 0
	s_mov_b32 m0, s27
	global_load_lds_dwordx4 v14, s[52:53]
	s_mov_b32 m0, s31
	s_nop 0
	global_load_lds_dwordx4 v140, s[52:53]
	ds_read_b128 v[136:139], v160
	ds_read_b128 v[148:151], v160 offset:1024
	ds_read_b128 v[156:159], v160 offset:2048
	ds_read_b128 v[160:163], v160 offset:3072
	ds_read_b128 v[164:167], v183
	ds_read_b128 v[168:171], v183 offset:1024
	ds_read_b128 v[172:175], v183 offset:2048
	ds_read_b128 v[184:187], v183 offset:3072
	ds_read_b128 v[188:191], v155 offset:32768
	ds_read_b128 v[192:195], v155 offset:33792
	ds_read_b128 v[196:199], v155 offset:34816
	ds_read_b128 v[200:203], v155 offset:35840
	ds_read_b128 v[214:217], v155 offset:36864
	ds_read_b128 v[218:221], v155 offset:37888
	ds_read_b128 v[222:225], v155 offset:38912
	ds_read_b128 v[226:229], v155 offset:39936
	s_waitcnt vmcnt(8)
	s_waitcnt lgkmcnt(0)
	s_barrier
	s_setprio 1
	s_waitcnt lgkmcnt(0)
	v_mfma_f32_16x16x32_bf16 v[132:135], v[136:139], v[188:191], v[132:135]
	v_mfma_f32_16x16x32_bf16 v[128:131], v[156:159], v[188:191], v[128:131]
	v_mfma_f32_16x16x32_bf16 v[116:119], v[136:139], v[196:199], v[116:119]
	v_mfma_f32_16x16x32_bf16 v[112:115], v[156:159], v[196:199], v[112:115]
	v_mfma_f32_16x16x32_bf16 v[100:103], v[136:139], v[214:217], v[100:103]
	v_mfma_f32_16x16x32_bf16 v[96:99], v[156:159], v[214:217], v[96:99]
	v_mfma_f32_16x16x32_bf16 v[84:87], v[136:139], v[222:225], v[84:87]
	v_mfma_f32_16x16x32_bf16 v[80:83], v[156:159], v[222:225], v[80:83]
	v_mfma_f32_16x16x32_bf16 v[132:135], v[148:151], v[192:195], v[132:135]
	v_mfma_f32_16x16x32_bf16 v[128:131], v[160:163], v[192:195], v[128:131]
	v_mfma_f32_16x16x32_bf16 v[116:119], v[148:151], v[200:203], v[116:119]
	v_mfma_f32_16x16x32_bf16 v[112:115], v[160:163], v[200:203], v[112:115]
	v_mfma_f32_16x16x32_bf16 v[100:103], v[148:151], v[218:221], v[100:103]
	v_mfma_f32_16x16x32_bf16 v[96:99], v[160:163], v[218:221], v[96:99]
	v_mfma_f32_16x16x32_bf16 v[84:87], v[148:151], v[226:229], v[84:87]
	v_mfma_f32_16x16x32_bf16 v[80:83], v[160:163], v[226:229], v[80:83]
	s_setprio 0
	s_setprio 1
	v_mfma_f32_16x16x32_bf16 v[124:127], v[164:167], v[188:191], v[124:127]
	v_mfma_f32_16x16x32_bf16 v[120:123], v[172:175], v[188:191], v[120:123]
	v_mfma_f32_16x16x32_bf16 v[108:111], v[164:167], v[196:199], v[108:111]
	v_mfma_f32_16x16x32_bf16 v[104:107], v[172:175], v[196:199], v[104:107]
	v_mfma_f32_16x16x32_bf16 v[92:95], v[164:167], v[214:217], v[92:95]
	v_mfma_f32_16x16x32_bf16 v[88:91], v[172:175], v[214:217], v[88:91]
	v_mfma_f32_16x16x32_bf16 v[76:79], v[164:167], v[222:225], v[76:79]
	v_mfma_f32_16x16x32_bf16 v[72:75], v[172:175], v[222:225], v[72:75]
	v_mfma_f32_16x16x32_bf16 v[124:127], v[168:171], v[192:195], v[124:127]
	v_mfma_f32_16x16x32_bf16 v[120:123], v[184:187], v[192:195], v[120:123]
	v_mfma_f32_16x16x32_bf16 v[108:111], v[168:171], v[200:203], v[108:111]
	v_mfma_f32_16x16x32_bf16 v[104:107], v[184:187], v[200:203], v[104:107]
	v_mfma_f32_16x16x32_bf16 v[92:95], v[168:171], v[218:221], v[92:95]
	v_mfma_f32_16x16x32_bf16 v[88:91], v[184:187], v[218:221], v[88:91]
	v_mfma_f32_16x16x32_bf16 v[76:79], v[168:171], v[226:229], v[76:79]
	v_mfma_f32_16x16x32_bf16 v[72:75], v[184:187], v[226:229], v[72:75]
	s_setprio 0
	s_barrier
	s_add_i32 s35, s35, s20
	s_mov_b32 m0, s35
	global_load_lds_dwordx4 v34, s[98:99]
	s_add_i32 m0, s35, 0x2000
	s_add_u32 s50, s50, 0x80080
	s_addc_u32 s51, s51, 0
	s_add_i32 s35, s72, s20
	global_load_lds_dwordx4 v142, s[98:99]
	s_mov_b32 m0, s35
	s_nop 0
	global_load_lds_dwordx4 v34, s[50:51]
	s_add_i32 m0, s35, 0x2000
	s_nop 0
	global_load_lds_dwordx4 v142, s[50:51]
	s_mov_b32 m0, s60
	s_nop 0
	global_load_lds_dwordx4 v14, s[100:101]
	s_mov_b32 m0, s61
	s_nop 0
	global_load_lds_dwordx4 v140, s[100:101]
	ds_read_b128 v[188:191], v155 offset:49152
	ds_read_b128 v[192:195], v155 offset:50176
	ds_read_b128 v[196:199], v155 offset:51200
	ds_read_b128 v[200:203], v155 offset:52224
	ds_read_b128 v[214:217], v155 offset:53248
	ds_read_b128 v[218:221], v155 offset:54272
	ds_read_b128 v[222:225], v155 offset:55296
	ds_read_b128 v[226:229], v155 offset:56320
	s_waitcnt vmcnt(8)
	s_waitcnt lgkmcnt(0)
	s_barrier
	s_setprio 1
	s_waitcnt lgkmcnt(0)
	v_mfma_f32_16x16x32_bf16 v[68:71], v[136:139], v[188:191], v[68:71]
	v_mfma_f32_16x16x32_bf16 v[64:67], v[156:159], v[188:191], v[64:67]
	v_mfma_f32_16x16x32_bf16 v[52:55], v[136:139], v[196:199], v[52:55]
	v_mfma_f32_16x16x32_bf16 v[48:51], v[156:159], v[196:199], v[48:51]
	v_mfma_f32_16x16x32_bf16 v[36:39], v[136:139], v[214:217], v[36:39]
	v_mfma_f32_16x16x32_bf16 v[30:33], v[156:159], v[214:217], v[30:33]
	v_mfma_f32_16x16x32_bf16 v[18:21], v[136:139], v[222:225], v[18:21]
	v_mfma_f32_16x16x32_bf16 v[10:13], v[156:159], v[222:225], v[10:13]
	v_mfma_f32_16x16x32_bf16 v[68:71], v[148:151], v[192:195], v[68:71]
	v_mfma_f32_16x16x32_bf16 v[64:67], v[160:163], v[192:195], v[64:67]
	v_mfma_f32_16x16x32_bf16 v[52:55], v[148:151], v[200:203], v[52:55]
	v_mfma_f32_16x16x32_bf16 v[48:51], v[160:163], v[200:203], v[48:51]
	v_mfma_f32_16x16x32_bf16 v[36:39], v[148:151], v[218:221], v[36:39]
	v_mfma_f32_16x16x32_bf16 v[30:33], v[160:163], v[218:221], v[30:33]
	v_mfma_f32_16x16x32_bf16 v[18:21], v[148:151], v[226:229], v[18:21]
	v_mfma_f32_16x16x32_bf16 v[10:13], v[160:163], v[226:229], v[10:13]
	s_setprio 0
	s_setprio 1
	v_mfma_f32_16x16x32_bf16 v[60:63], v[164:167], v[188:191], v[60:63]
	v_mfma_f32_16x16x32_bf16 v[56:59], v[172:175], v[188:191], v[56:59]
	v_mfma_f32_16x16x32_bf16 v[44:47], v[164:167], v[196:199], v[44:47]
	v_mfma_f32_16x16x32_bf16 v[40:43], v[172:175], v[196:199], v[40:43]
	v_mfma_f32_16x16x32_bf16 v[26:29], v[164:167], v[214:217], v[26:29]
	v_mfma_f32_16x16x32_bf16 v[22:25], v[172:175], v[214:217], v[22:25]
	v_mfma_f32_16x16x32_bf16 v[6:9], v[164:167], v[222:225], v[6:9]
	v_mfma_f32_16x16x32_bf16 v[2:5], v[172:175], v[222:225], v[2:5]
	v_mfma_f32_16x16x32_bf16 v[60:63], v[168:171], v[192:195], v[60:63]
	v_mfma_f32_16x16x32_bf16 v[56:59], v[184:187], v[192:195], v[56:59]
	v_mfma_f32_16x16x32_bf16 v[44:47], v[168:171], v[200:203], v[44:47]
	v_mfma_f32_16x16x32_bf16 v[40:43], v[184:187], v[200:203], v[40:43]
	v_mfma_f32_16x16x32_bf16 v[26:29], v[168:171], v[218:221], v[26:29]
	v_mfma_f32_16x16x32_bf16 v[22:25], v[184:187], v[218:221], v[22:25]
	v_mfma_f32_16x16x32_bf16 v[6:9], v[168:171], v[226:229], v[6:9]
	v_mfma_f32_16x16x32_bf16 v[2:5], v[184:187], v[226:229], v[2:5]
	s_setprio 0
	s_barrier
	s_add_u32 s48, s48, 0x100
	s_addc_u32 s49, s49, 0
	s_add_u32 s13, s13, 0x100
	s_addc_u32 s29, s29, 0
	s_cmp_ge_i32 s39, s71
	s_mov_b32 s35, s39
	s_cbranch_scc0 .LBB0_1508
	s_and_b64 vcc, exec, s[10:11]
	s_cbranch_vccz .LBB0_1511

.LBB0_1664:
	s_add_u32 s44, s42, 0xfff80080
	s_addc_u32 s45, s43, -1
	s_add_i32 s64, 0, 0x10000
	s_cmp_eq_u32 s61, 28
	s_cselect_b32 s47, s29, s45
	s_cselect_b32 s46, s53, s44
	v_add_u32_e32 v151, s64, v141
	s_cselect_b32 s45, s13, s60
	s_cselect_b32 s44, s54, s55
	s_add_i32 s67, 0, 0x14000
	s_add_i32 m0, s25, 0xc000
	global_load_lds_dwordx4 v142, s[42:43]
	s_add_i32 m0, s25, 0xe000
	s_nop 0
	global_load_lds_dwordx4 v144, s[42:43]
	ds_read_b128 v[162:165], v151
	ds_read_b128 v[166:169], v151 offset:1024
	ds_read_b128 v[170:173], v151 offset:2048
	ds_read_b128 v[174:177], v151 offset:3072
	v_add_u32_e32 v151, s67, v141
	ds_read_b128 v[184:187], v151
	ds_read_b128 v[188:191], v151 offset:1024
	ds_read_b128 v[192:195], v151 offset:2048
	ds_read_b128 v[196:199], v151 offset:3072
	ds_read_b128 v[200:203], v149
	ds_read_b128 v[214:217], v149 offset:1024
	ds_read_b128 v[218:221], v149 offset:2048
	ds_read_b128 v[222:225], v149 offset:3072
	ds_read_b128 v[226:229], v149 offset:4096
	ds_read_b128 v[230:233], v149 offset:5120
	ds_read_b128 v[234:237], v149 offset:6144
	ds_read_b128 v[238:241], v149 offset:7168
	s_waitcnt vmcnt(8)
	s_waitcnt lgkmcnt(0)
	s_barrier
	s_setprio 1
	s_waitcnt lgkmcnt(0)
	v_mfma_f32_16x16x32_bf16 v[132:135], v[162:165], v[200:203], v[132:135]
	v_mfma_f32_16x16x32_bf16 v[128:131], v[170:173], v[200:203], v[128:131]
	v_mfma_f32_16x16x32_bf16 v[116:119], v[162:165], v[218:221], v[116:119]
	v_mfma_f32_16x16x32_bf16 v[112:115], v[170:173], v[218:221], v[112:115]
	v_mfma_f32_16x16x32_bf16 v[100:103], v[162:165], v[226:229], v[100:103]
	v_mfma_f32_16x16x32_bf16 v[96:99], v[170:173], v[226:229], v[96:99]
	v_mfma_f32_16x16x32_bf16 v[84:87], v[162:165], v[234:237], v[84:87]
	v_mfma_f32_16x16x32_bf16 v[80:83], v[170:173], v[234:237], v[80:83]
	v_mfma_f32_16x16x32_bf16 v[132:135], v[166:169], v[214:217], v[132:135]
	v_mfma_f32_16x16x32_bf16 v[128:131], v[174:177], v[214:217], v[128:131]
	v_mfma_f32_16x16x32_bf16 v[116:119], v[166:169], v[222:225], v[116:119]
	v_mfma_f32_16x16x32_bf16 v[112:115], v[174:177], v[222:225], v[112:115]
	v_mfma_f32_16x16x32_bf16 v[100:103], v[166:169], v[230:233], v[100:103]
	v_mfma_f32_16x16x32_bf16 v[96:99], v[174:177], v[230:233], v[96:99]
	v_mfma_f32_16x16x32_bf16 v[84:87], v[166:169], v[238:241], v[84:87]
	v_mfma_f32_16x16x32_bf16 v[80:83], v[174:177], v[238:241], v[80:83]
	s_setprio 0
	s_setprio 1
	v_mfma_f32_16x16x32_bf16 v[124:127], v[184:187], v[200:203], v[124:127]
	v_mfma_f32_16x16x32_bf16 v[120:123], v[192:195], v[200:203], v[120:123]
	v_mfma_f32_16x16x32_bf16 v[108:111], v[184:187], v[218:221], v[108:111]
	v_mfma_f32_16x16x32_bf16 v[104:107], v[192:195], v[218:221], v[104:107]
	v_mfma_f32_16x16x32_bf16 v[92:95], v[184:187], v[226:229], v[92:95]
	v_mfma_f32_16x16x32_bf16 v[88:91], v[192:195], v[226:229], v[88:91]
	v_mfma_f32_16x16x32_bf16 v[76:79], v[184:187], v[234:237], v[76:79]
	v_mfma_f32_16x16x32_bf16 v[72:75], v[192:195], v[234:237], v[72:75]
	v_mfma_f32_16x16x32_bf16 v[124:127], v[188:191], v[214:217], v[124:127]
	v_mfma_f32_16x16x32_bf16 v[120:123], v[196:199], v[214:217], v[120:123]
	v_mfma_f32_16x16x32_bf16 v[108:111], v[188:191], v[222:225], v[108:111]
	v_mfma_f32_16x16x32_bf16 v[104:107], v[196:199], v[222:225], v[104:107]
	v_mfma_f32_16x16x32_bf16 v[92:95], v[188:191], v[230:233], v[92:95]
	v_mfma_f32_16x16x32_bf16 v[88:91], v[196:199], v[230:233], v[88:91]
	v_mfma_f32_16x16x32_bf16 v[76:79], v[188:191], v[238:241], v[76:79]
	v_mfma_f32_16x16x32_bf16 v[72:75], v[196:199], v[238:241], v[72:75]
	s_setprio 0
	s_barrier
	s_add_u32 s98, s44, s22
	s_addc_u32 s99, s45, s23
	s_add_u32 s100, s46, s22
	s_addc_u32 s101, s47, s23
	s_add_i32 s64, s64, s20
	s_mov_b32 m0, s64
	global_load_lds_dwordx4 v34, s[44:45]
	s_add_i32 m0, s64, 0x2000
	s_add_u32 s64, s44, 0x80000
	s_addc_u32 s65, s45, 0
	s_add_i32 s67, s67, s20
	global_load_lds_dwordx4 v14, s[44:45]
	s_mov_b32 m0, s67
	global_load_lds_dwordx4 v34, s[64:65]
	s_add_i32 m0, s67, 0x2000
	s_nop 0
	global_load_lds_dwordx4 v14, s[64:65]
	s_mov_b32 m0, s25
	s_nop 0
	global_load_lds_dwordx4 v138, s[46:47]
	s_mov_b32 m0, s26
	s_nop 0
	global_load_lds_dwordx4 v136, s[46:47]
	ds_read_b128 v[200:203], v149 offset:16384
	ds_read_b128 v[214:217], v149 offset:17408
	ds_read_b128 v[218:221], v149 offset:18432
	ds_read_b128 v[222:225], v149 offset:19456
	ds_read_b128 v[226:229], v149 offset:20480
	ds_read_b128 v[230:233], v149 offset:21504
	ds_read_b128 v[234:237], v149 offset:22528
	ds_read_b128 v[238:241], v149 offset:23552
	s_waitcnt vmcnt(8)
	s_waitcnt lgkmcnt(0)
	s_barrier
	s_setprio 1
	s_waitcnt lgkmcnt(0)
	v_mfma_f32_16x16x32_bf16 v[68:71], v[162:165], v[200:203], v[68:71]
	v_mfma_f32_16x16x32_bf16 v[64:67], v[170:173], v[200:203], v[64:67]
	v_mfma_f32_16x16x32_bf16 v[52:55], v[162:165], v[218:221], v[52:55]
	v_mfma_f32_16x16x32_bf16 v[48:51], v[170:173], v[218:221], v[48:51]
	v_mfma_f32_16x16x32_bf16 v[36:39], v[162:165], v[226:229], v[36:39]
	v_mfma_f32_16x16x32_bf16 v[30:33], v[170:173], v[226:229], v[30:33]
	v_mfma_f32_16x16x32_bf16 v[18:21], v[162:165], v[234:237], v[18:21]
	v_mfma_f32_16x16x32_bf16 v[10:13], v[170:173], v[234:237], v[10:13]
	v_mfma_f32_16x16x32_bf16 v[68:71], v[166:169], v[214:217], v[68:71]
	v_mfma_f32_16x16x32_bf16 v[64:67], v[174:177], v[214:217], v[64:67]
	v_mfma_f32_16x16x32_bf16 v[52:55], v[166:169], v[222:225], v[52:55]
	v_mfma_f32_16x16x32_bf16 v[48:51], v[174:177], v[222:225], v[48:51]
	v_mfma_f32_16x16x32_bf16 v[36:39], v[166:169], v[230:233], v[36:39]
	v_mfma_f32_16x16x32_bf16 v[30:33], v[174:177], v[230:233], v[30:33]
	v_mfma_f32_16x16x32_bf16 v[18:21], v[166:169], v[238:241], v[18:21]
	v_mfma_f32_16x16x32_bf16 v[10:13], v[174:177], v[238:241], v[10:13]
	s_setprio 0
	s_setprio 1
	v_mfma_f32_16x16x32_bf16 v[60:63], v[184:187], v[200:203], v[60:63]
	v_mfma_f32_16x16x32_bf16 v[56:59], v[192:195], v[200:203], v[56:59]
	v_mfma_f32_16x16x32_bf16 v[44:47], v[184:187], v[218:221], v[44:47]
	v_mfma_f32_16x16x32_bf16 v[40:43], v[192:195], v[218:221], v[40:43]
	v_mfma_f32_16x16x32_bf16 v[26:29], v[184:187], v[226:229], v[26:29]
	v_mfma_f32_16x16x32_bf16 v[22:25], v[192:195], v[226:229], v[22:25]
	v_mfma_f32_16x16x32_bf16 v[6:9], v[184:187], v[234:237], v[6:9]
	v_mfma_f32_16x16x32_bf16 v[2:5], v[192:195], v[234:237], v[2:5]
	v_mfma_f32_16x16x32_bf16 v[60:63], v[188:191], v[214:217], v[60:63]
	v_mfma_f32_16x16x32_bf16 v[56:59], v[196:199], v[214:217], v[56:59]
	v_mfma_f32_16x16x32_bf16 v[44:47], v[188:191], v[222:225], v[44:47]
	v_mfma_f32_16x16x32_bf16 v[40:43], v[196:199], v[222:225], v[40:43]
	v_mfma_f32_16x16x32_bf16 v[26:29], v[188:191], v[230:233], v[26:29]
	v_mfma_f32_16x16x32_bf16 v[22:25], v[196:199], v[230:233], v[22:25]
	v_mfma_f32_16x16x32_bf16 v[6:9], v[188:191], v[238:241], v[6:9]
	v_mfma_f32_16x16x32_bf16 v[2:5], v[196:199], v[238:241], v[2:5]
	s_setprio 0
	s_barrier
	s_add_i32 s64, 0, 0x18000
	v_add_u32_e32 v151, s64, v141
	s_add_i32 s65, 0, 0x1c000
	s_add_u32 s46, s46, 0x80000
	s_addc_u32 s47, s47, 0
	s_mov_b32 m0, s27
	global_load_lds_dwordx4 v138, s[46:47]
	s_mov_b32 m0, s31
	s_nop 0
	global_load_lds_dwordx4 v136, s[46:47]
	ds_read_b128 v[162:165], v151
	ds_read_b128 v[166:169], v151 offset:1024
	ds_read_b128 v[170:173], v151 offset:2048
	ds_read_b128 v[174:177], v151 offset:3072
	v_add_u32_e32 v151, s65, v141
	ds_read_b128 v[184:187], v151
	ds_read_b128 v[188:191], v151 offset:1024
	ds_read_b128 v[192:195], v151 offset:2048
	ds_read_b128 v[196:199], v151 offset:3072
	ds_read_b128 v[200:203], v149 offset:32768
	ds_read_b128 v[214:217], v149 offset:33792
	ds_read_b128 v[218:221], v149 offset:34816
	ds_read_b128 v[222:225], v149 offset:35840
	ds_read_b128 v[226:229], v149 offset:36864
	ds_read_b128 v[230:233], v149 offset:37888
	ds_read_b128 v[234:237], v149 offset:38912
	ds_read_b128 v[238:241], v149 offset:39936
	s_waitcnt vmcnt(8)
	s_waitcnt lgkmcnt(0)
	s_barrier
	s_setprio 1
	s_waitcnt lgkmcnt(0)
	v_mfma_f32_16x16x32_bf16 v[132:135], v[162:165], v[200:203], v[132:135]
	v_mfma_f32_16x16x32_bf16 v[128:131], v[170:173], v[200:203], v[128:131]
	v_mfma_f32_16x16x32_bf16 v[116:119], v[162:165], v[218:221], v[116:119]
	v_mfma_f32_16x16x32_bf16 v[112:115], v[170:173], v[218:221], v[112:115]
	v_mfma_f32_16x16x32_bf16 v[100:103], v[162:165], v[226:229], v[100:103]
	v_mfma_f32_16x16x32_bf16 v[96:99], v[170:173], v[226:229], v[96:99]
	v_mfma_f32_16x16x32_bf16 v[84:87], v[162:165], v[234:237], v[84:87]
	v_mfma_f32_16x16x32_bf16 v[80:83], v[170:173], v[234:237], v[80:83]
	v_mfma_f32_16x16x32_bf16 v[132:135], v[166:169], v[214:217], v[132:135]
	v_mfma_f32_16x16x32_bf16 v[128:131], v[174:177], v[214:217], v[128:131]
	v_mfma_f32_16x16x32_bf16 v[116:119], v[166:169], v[222:225], v[116:119]
	v_mfma_f32_16x16x32_bf16 v[112:115], v[174:177], v[222:225], v[112:115]
	v_mfma_f32_16x16x32_bf16 v[100:103], v[166:169], v[230:233], v[100:103]
	v_mfma_f32_16x16x32_bf16 v[96:99], v[174:177], v[230:233], v[96:99]
	v_mfma_f32_16x16x32_bf16 v[84:87], v[166:169], v[238:241], v[84:87]
	v_mfma_f32_16x16x32_bf16 v[80:83], v[174:177], v[238:241], v[80:83]
	s_setprio 0
	s_setprio 1
	v_mfma_f32_16x16x32_bf16 v[124:127], v[184:187], v[200:203], v[124:127]
	v_mfma_f32_16x16x32_bf16 v[120:123], v[192:195], v[200:203], v[120:123]
	v_mfma_f32_16x16x32_bf16 v[108:111], v[184:187], v[218:221], v[108:111]
	v_mfma_f32_16x16x32_bf16 v[104:107], v[192:195], v[218:221], v[104:107]
	v_mfma_f32_16x16x32_bf16 v[92:95], v[184:187], v[226:229], v[92:95]
	v_mfma_f32_16x16x32_bf16 v[88:91], v[192:195], v[226:229], v[88:91]
	v_mfma_f32_16x16x32_bf16 v[76:79], v[184:187], v[234:237], v[76:79]
	v_mfma_f32_16x16x32_bf16 v[72:75], v[192:195], v[234:237], v[72:75]
	v_mfma_f32_16x16x32_bf16 v[124:127], v[188:191], v[214:217], v[124:127]
	v_mfma_f32_16x16x32_bf16 v[120:123], v[196:199], v[214:217], v[120:123]
	v_mfma_f32_16x16x32_bf16 v[108:111], v[188:191], v[222:225], v[108:111]
	v_mfma_f32_16x16x32_bf16 v[104:107], v[196:199], v[222:225], v[104:107]
	v_mfma_f32_16x16x32_bf16 v[92:95], v[188:191], v[230:233], v[92:95]
	v_mfma_f32_16x16x32_bf16 v[88:91], v[196:199], v[230:233], v[88:91]
	v_mfma_f32_16x16x32_bf16 v[76:79], v[188:191], v[238:241], v[76:79]
	v_mfma_f32_16x16x32_bf16 v[72:75], v[196:199], v[238:241], v[72:75]
	s_setprio 0
	s_barrier
	s_add_i32 s46, s64, s20
	s_mov_b32 m0, s46
	global_load_lds_dwordx4 v34, s[98:99]
	s_add_i32 m0, s46, 0x2000
	s_add_u32 s44, s44, 0x80080
	s_addc_u32 s45, s45, 0
	s_add_i32 s46, s65, s20
	global_load_lds_dwordx4 v14, s[98:99]
	s_mov_b32 m0, s46
	s_nop 0
	global_load_lds_dwordx4 v34, s[44:45]
	s_add_i32 m0, s46, 0x2000
	s_nop 0
	global_load_lds_dwordx4 v14, s[44:45]
	s_mov_b32 m0, s48
	s_nop 0
	global_load_lds_dwordx4 v138, s[100:101]
	s_mov_b32 m0, s49
	s_nop 0
	global_load_lds_dwordx4 v136, s[100:101]
	ds_read_b128 v[200:203], v149 offset:49152
	ds_read_b128 v[214:217], v149 offset:50176
	ds_read_b128 v[218:221], v149 offset:51200
	ds_read_b128 v[222:225], v149 offset:52224
	ds_read_b128 v[226:229], v149 offset:53248
	ds_read_b128 v[230:233], v149 offset:54272
	ds_read_b128 v[234:237], v149 offset:55296
	ds_read_b128 v[238:241], v149 offset:56320
	s_waitcnt vmcnt(8)
	s_waitcnt lgkmcnt(0)
	s_barrier
	s_setprio 1
	s_waitcnt lgkmcnt(0)
	v_mfma_f32_16x16x32_bf16 v[68:71], v[162:165], v[200:203], v[68:71]
	v_mfma_f32_16x16x32_bf16 v[64:67], v[170:173], v[200:203], v[64:67]
	v_mfma_f32_16x16x32_bf16 v[52:55], v[162:165], v[218:221], v[52:55]
	v_mfma_f32_16x16x32_bf16 v[48:51], v[170:173], v[218:221], v[48:51]
	v_mfma_f32_16x16x32_bf16 v[36:39], v[162:165], v[226:229], v[36:39]
	v_mfma_f32_16x16x32_bf16 v[30:33], v[170:173], v[226:229], v[30:33]
	v_mfma_f32_16x16x32_bf16 v[18:21], v[162:165], v[234:237], v[18:21]
	v_mfma_f32_16x16x32_bf16 v[10:13], v[170:173], v[234:237], v[10:13]
	v_mfma_f32_16x16x32_bf16 v[68:71], v[166:169], v[214:217], v[68:71]
	v_mfma_f32_16x16x32_bf16 v[64:67], v[174:177], v[214:217], v[64:67]
	v_mfma_f32_16x16x32_bf16 v[52:55], v[166:169], v[222:225], v[52:55]
	v_mfma_f32_16x16x32_bf16 v[48:51], v[174:177], v[222:225], v[48:51]
	v_mfma_f32_16x16x32_bf16 v[36:39], v[166:169], v[230:233], v[36:39]
	v_mfma_f32_16x16x32_bf16 v[30:33], v[174:177], v[230:233], v[30:33]
	v_mfma_f32_16x16x32_bf16 v[18:21], v[166:169], v[238:241], v[18:21]
	v_mfma_f32_16x16x32_bf16 v[10:13], v[174:177], v[238:241], v[10:13]
	s_setprio 0
	s_setprio 1
	v_mfma_f32_16x16x32_bf16 v[60:63], v[184:187], v[200:203], v[60:63]
	v_mfma_f32_16x16x32_bf16 v[56:59], v[192:195], v[200:203], v[56:59]
	v_mfma_f32_16x16x32_bf16 v[44:47], v[184:187], v[218:221], v[44:47]
	v_mfma_f32_16x16x32_bf16 v[40:43], v[192:195], v[218:221], v[40:43]
	v_mfma_f32_16x16x32_bf16 v[26:29], v[184:187], v[226:229], v[26:29]
	v_mfma_f32_16x16x32_bf16 v[22:25], v[192:195], v[226:229], v[22:25]
	v_mfma_f32_16x16x32_bf16 v[6:9], v[184:187], v[234:237], v[6:9]
	v_mfma_f32_16x16x32_bf16 v[2:5], v[192:195], v[234:237], v[2:5]
	v_mfma_f32_16x16x32_bf16 v[60:63], v[188:191], v[214:217], v[60:63]
	v_mfma_f32_16x16x32_bf16 v[56:59], v[196:199], v[214:217], v[56:59]
	v_mfma_f32_16x16x32_bf16 v[44:47], v[188:191], v[222:225], v[44:47]
	v_mfma_f32_16x16x32_bf16 v[40:43], v[196:199], v[222:225], v[40:43]
	v_mfma_f32_16x16x32_bf16 v[26:29], v[188:191], v[230:233], v[26:29]
	v_mfma_f32_16x16x32_bf16 v[22:25], v[196:199], v[230:233], v[22:25]
	v_mfma_f32_16x16x32_bf16 v[6:9], v[188:191], v[238:241], v[6:9]
	v_mfma_f32_16x16x32_bf16 v[2:5], v[196:199], v[238:241], v[2:5]
	s_setprio 0
	s_barrier
	s_add_i32 s61, s61, 2
	s_add_u32 s42, s42, 0x100
	s_addc_u32 s43, s43, 0
	s_add_u32 s55, s55, 0x100
	s_addc_u32 s60, s60, 0
	s_cmp_gt_u32 s61, 29
	s_cbranch_scc0 .LBB0_1664
	s_and_b64 vcc, exec, s[10:11]
	s_cbranch_vccz .LBB0_1667
	s_barrier

.LBB0_1764:
	s_add_i32 vcc_lo, s44, 2
	s_add_u32 s42, s36, 0x100
	s_addc_u32 s43, s37, 0
	s_add_i32 s72, 0, 0x10000
	s_cmp_eq_u32 s11, s44
	s_cselect_b32 s47, s13, s43
	s_cselect_b32 s46, s12, s42
	s_cselect_b32 s45, s29, s71
	s_cselect_b32 s44, s28, s70
	s_add_i32 s73, 0, 0x14000
	v_add_u32_e32 v160, s72, v152
	v_add_u32_e32 v176, s73, v152
	s_add_i32 m0, s25, 0xc000
	global_load_lds_dwordx4 v144, s[36:37]
	s_add_i32 m0, s25, 0xe000
	s_nop 0
	global_load_lds_dwordx4 v146, s[36:37]
	ds_read_b128 v[136:139], v160
	ds_read_b128 v[148:151], v160 offset:1024
	ds_read_b128 v[156:159], v160 offset:2048
	ds_read_b128 v[160:163], v160 offset:3072
	ds_read_b128 v[164:167], v176
	ds_read_b128 v[168:171], v176 offset:1024
	ds_read_b128 v[172:175], v176 offset:2048
	ds_read_b128 v[184:187], v176 offset:3072
	ds_read_b128 v[188:191], v155
	ds_read_b128 v[192:195], v155 offset:1024
	ds_read_b128 v[196:199], v155 offset:2048
	ds_read_b128 v[200:203], v155 offset:3072
	ds_read_b128 v[214:217], v155 offset:4096
	ds_read_b128 v[218:221], v155 offset:5120
	ds_read_b128 v[222:225], v155 offset:6144
	ds_read_b128 v[226:229], v155 offset:7168
	s_waitcnt vmcnt(8)
	s_waitcnt lgkmcnt(0)
	s_barrier
	s_setprio 1
	s_waitcnt lgkmcnt(0)
	v_mfma_f32_16x16x32_bf16 v[132:135], v[136:139], v[188:191], v[132:135]
	v_mfma_f32_16x16x32_bf16 v[128:131], v[156:159], v[188:191], v[128:131]
	v_mfma_f32_16x16x32_bf16 v[116:119], v[136:139], v[196:199], v[116:119]
	v_mfma_f32_16x16x32_bf16 v[112:115], v[156:159], v[196:199], v[112:115]
	v_mfma_f32_16x16x32_bf16 v[100:103], v[136:139], v[214:217], v[100:103]
	v_mfma_f32_16x16x32_bf16 v[96:99], v[156:159], v[214:217], v[96:99]
	v_mfma_f32_16x16x32_bf16 v[84:87], v[136:139], v[222:225], v[84:87]
	v_mfma_f32_16x16x32_bf16 v[80:83], v[156:159], v[222:225], v[80:83]
	v_mfma_f32_16x16x32_bf16 v[132:135], v[148:151], v[192:195], v[132:135]
	v_mfma_f32_16x16x32_bf16 v[128:131], v[160:163], v[192:195], v[128:131]
	v_mfma_f32_16x16x32_bf16 v[116:119], v[148:151], v[200:203], v[116:119]
	v_mfma_f32_16x16x32_bf16 v[112:115], v[160:163], v[200:203], v[112:115]
	v_mfma_f32_16x16x32_bf16 v[100:103], v[148:151], v[218:221], v[100:103]
	v_mfma_f32_16x16x32_bf16 v[96:99], v[160:163], v[218:221], v[96:99]
	v_mfma_f32_16x16x32_bf16 v[84:87], v[148:151], v[226:229], v[84:87]
	v_mfma_f32_16x16x32_bf16 v[80:83], v[160:163], v[226:229], v[80:83]
	s_setprio 0
	s_setprio 1
	v_mfma_f32_16x16x32_bf16 v[124:127], v[164:167], v[188:191], v[124:127]
	v_mfma_f32_16x16x32_bf16 v[120:123], v[172:175], v[188:191], v[120:123]
	v_mfma_f32_16x16x32_bf16 v[108:111], v[164:167], v[196:199], v[108:111]
	v_mfma_f32_16x16x32_bf16 v[104:107], v[172:175], v[196:199], v[104:107]
	v_mfma_f32_16x16x32_bf16 v[92:95], v[164:167], v[214:217], v[92:95]
	v_mfma_f32_16x16x32_bf16 v[88:91], v[172:175], v[214:217], v[88:91]
	v_mfma_f32_16x16x32_bf16 v[76:79], v[164:167], v[222:225], v[76:79]
	v_mfma_f32_16x16x32_bf16 v[72:75], v[172:175], v[222:225], v[72:75]
	v_mfma_f32_16x16x32_bf16 v[124:127], v[168:171], v[192:195], v[124:127]
	v_mfma_f32_16x16x32_bf16 v[120:123], v[184:187], v[192:195], v[120:123]
	v_mfma_f32_16x16x32_bf16 v[108:111], v[168:171], v[200:203], v[108:111]
	v_mfma_f32_16x16x32_bf16 v[104:107], v[184:187], v[200:203], v[104:107]
	v_mfma_f32_16x16x32_bf16 v[92:95], v[168:171], v[218:221], v[92:95]
	v_mfma_f32_16x16x32_bf16 v[88:91], v[184:187], v[218:221], v[88:91]
	v_mfma_f32_16x16x32_bf16 v[76:79], v[168:171], v[226:229], v[76:79]
	v_mfma_f32_16x16x32_bf16 v[72:75], v[184:187], v[226:229], v[72:75]
	s_setprio 0
	s_barrier
	s_add_u32 s98, s44, s22
	s_addc_u32 s99, s45, s23
	s_add_u32 s100, s46, s22
	s_addc_u32 s101, s47, s23
	s_add_i32 s36, s72, s20
	s_mov_b32 m0, s36
	global_load_lds_dwordx4 v34, s[44:45]
	s_add_i32 m0, s36, 0x2000
	s_add_u32 s36, s44, 0x160000
	s_addc_u32 s37, s45, 0
	s_add_i32 s72, s73, s20
	global_load_lds_dwordx4 v142, s[44:45]
	s_mov_b32 m0, s72
	global_load_lds_dwordx4 v34, s[36:37]
	s_add_i32 m0, s72, 0x2000
	s_nop 0
	global_load_lds_dwordx4 v142, s[36:37]
	s_mov_b32 m0, s25
	s_nop 0
	global_load_lds_dwordx4 v14, s[46:47]
	s_mov_b32 m0, s26
	s_nop 0
	global_load_lds_dwordx4 v140, s[46:47]
	ds_read_b128 v[188:191], v155 offset:16384
	ds_read_b128 v[192:195], v155 offset:17408
	ds_read_b128 v[196:199], v155 offset:18432
	ds_read_b128 v[200:203], v155 offset:19456
	ds_read_b128 v[214:217], v155 offset:20480
	ds_read_b128 v[218:221], v155 offset:21504
	ds_read_b128 v[222:225], v155 offset:22528
	ds_read_b128 v[226:229], v155 offset:23552
	s_waitcnt vmcnt(8)
	s_waitcnt lgkmcnt(0)
	s_barrier
	s_setprio 1
	s_waitcnt lgkmcnt(0)
	v_mfma_f32_16x16x32_bf16 v[68:71], v[136:139], v[188:191], v[68:71]
	v_mfma_f32_16x16x32_bf16 v[64:67], v[156:159], v[188:191], v[64:67]
	v_mfma_f32_16x16x32_bf16 v[52:55], v[136:139], v[196:199], v[52:55]
	v_mfma_f32_16x16x32_bf16 v[48:51], v[156:159], v[196:199], v[48:51]
	v_mfma_f32_16x16x32_bf16 v[36:39], v[136:139], v[214:217], v[36:39]
	v_mfma_f32_16x16x32_bf16 v[30:33], v[156:159], v[214:217], v[30:33]
	v_mfma_f32_16x16x32_bf16 v[18:21], v[136:139], v[222:225], v[18:21]
	v_mfma_f32_16x16x32_bf16 v[10:13], v[156:159], v[222:225], v[10:13]
	v_mfma_f32_16x16x32_bf16 v[68:71], v[148:151], v[192:195], v[68:71]
	v_mfma_f32_16x16x32_bf16 v[64:67], v[160:163], v[192:195], v[64:67]
	v_mfma_f32_16x16x32_bf16 v[52:55], v[148:151], v[200:203], v[52:55]
	v_mfma_f32_16x16x32_bf16 v[48:51], v[160:163], v[200:203], v[48:51]
	v_mfma_f32_16x16x32_bf16 v[36:39], v[148:151], v[218:221], v[36:39]
	v_mfma_f32_16x16x32_bf16 v[30:33], v[160:163], v[218:221], v[30:33]
	v_mfma_f32_16x16x32_bf16 v[18:21], v[148:151], v[226:229], v[18:21]
	v_mfma_f32_16x16x32_bf16 v[10:13], v[160:163], v[226:229], v[10:13]
	s_setprio 0
	s_setprio 1
	v_mfma_f32_16x16x32_bf16 v[60:63], v[164:167], v[188:191], v[60:63]
	v_mfma_f32_16x16x32_bf16 v[56:59], v[172:175], v[188:191], v[56:59]
	v_mfma_f32_16x16x32_bf16 v[44:47], v[164:167], v[196:199], v[44:47]
	v_mfma_f32_16x16x32_bf16 v[40:43], v[172:175], v[196:199], v[40:43]
	v_mfma_f32_16x16x32_bf16 v[26:29], v[164:167], v[214:217], v[26:29]
	v_mfma_f32_16x16x32_bf16 v[22:25], v[172:175], v[214:217], v[22:25]
	v_mfma_f32_16x16x32_bf16 v[6:9], v[164:167], v[222:225], v[6:9]
	v_mfma_f32_16x16x32_bf16 v[2:5], v[172:175], v[222:225], v[2:5]
	v_mfma_f32_16x16x32_bf16 v[60:63], v[168:171], v[192:195], v[60:63]
	v_mfma_f32_16x16x32_bf16 v[56:59], v[184:187], v[192:195], v[56:59]
	v_mfma_f32_16x16x32_bf16 v[44:47], v[168:171], v[200:203], v[44:47]
	v_mfma_f32_16x16x32_bf16 v[40:43], v[184:187], v[200:203], v[40:43]
	v_mfma_f32_16x16x32_bf16 v[26:29], v[168:171], v[218:221], v[26:29]
	v_mfma_f32_16x16x32_bf16 v[22:25], v[184:187], v[218:221], v[22:25]
	v_mfma_f32_16x16x32_bf16 v[6:9], v[168:171], v[226:229], v[6:9]
	v_mfma_f32_16x16x32_bf16 v[2:5], v[184:187], v[226:229], v[2:5]
	s_setprio 0
	s_barrier
	s_add_i32 s72, 0, 0x18000
	s_add_i32 s73, 0, 0x1c000
	v_add_u32_e32 v160, s72, v152
	v_add_u32_e32 v183, s73, v152
	s_add_u32 s36, s46, 0x160000
	s_addc_u32 s37, s47, 0
	s_mov_b32 m0, s27
	global_load_lds_dwordx4 v14, s[36:37]
	s_mov_b32 m0, s31
	s_nop 0
	global_load_lds_dwordx4 v140, s[36:37]
	ds_read_b128 v[136:139], v160
	ds_read_b128 v[148:151], v160 offset:1024
	ds_read_b128 v[156:159], v160 offset:2048
	ds_read_b128 v[160:163], v160 offset:3072
	ds_read_b128 v[164:167], v183
	ds_read_b128 v[168:171], v183 offset:1024
	ds_read_b128 v[172:175], v183 offset:2048
	ds_read_b128 v[184:187], v183 offset:3072
	ds_read_b128 v[188:191], v155 offset:32768
	ds_read_b128 v[192:195], v155 offset:33792
	ds_read_b128 v[196:199], v155 offset:34816
	ds_read_b128 v[200:203], v155 offset:35840
	ds_read_b128 v[214:217], v155 offset:36864
	ds_read_b128 v[218:221], v155 offset:37888
	ds_read_b128 v[222:225], v155 offset:38912
	ds_read_b128 v[226:229], v155 offset:39936
	s_waitcnt vmcnt(8)
	s_waitcnt lgkmcnt(0)
	s_barrier
	s_setprio 1
	s_waitcnt lgkmcnt(0)
	v_mfma_f32_16x16x32_bf16 v[132:135], v[136:139], v[188:191], v[132:135]
	v_mfma_f32_16x16x32_bf16 v[128:131], v[156:159], v[188:191], v[128:131]
	v_mfma_f32_16x16x32_bf16 v[116:119], v[136:139], v[196:199], v[116:119]
	v_mfma_f32_16x16x32_bf16 v[112:115], v[156:159], v[196:199], v[112:115]
	v_mfma_f32_16x16x32_bf16 v[100:103], v[136:139], v[214:217], v[100:103]
	v_mfma_f32_16x16x32_bf16 v[96:99], v[156:159], v[214:217], v[96:99]
	v_mfma_f32_16x16x32_bf16 v[84:87], v[136:139], v[222:225], v[84:87]
	v_mfma_f32_16x16x32_bf16 v[80:83], v[156:159], v[222:225], v[80:83]
	v_mfma_f32_16x16x32_bf16 v[132:135], v[148:151], v[192:195], v[132:135]
	v_mfma_f32_16x16x32_bf16 v[128:131], v[160:163], v[192:195], v[128:131]
	v_mfma_f32_16x16x32_bf16 v[116:119], v[148:151], v[200:203], v[116:119]
	v_mfma_f32_16x16x32_bf16 v[112:115], v[160:163], v[200:203], v[112:115]
	v_mfma_f32_16x16x32_bf16 v[100:103], v[148:151], v[218:221], v[100:103]
	v_mfma_f32_16x16x32_bf16 v[96:99], v[160:163], v[218:221], v[96:99]
	v_mfma_f32_16x16x32_bf16 v[84:87], v[148:151], v[226:229], v[84:87]
	v_mfma_f32_16x16x32_bf16 v[80:83], v[160:163], v[226:229], v[80:83]
	s_setprio 0
	s_setprio 1
	v_mfma_f32_16x16x32_bf16 v[124:127], v[164:167], v[188:191], v[124:127]
	v_mfma_f32_16x16x32_bf16 v[120:123], v[172:175], v[188:191], v[120:123]
	v_mfma_f32_16x16x32_bf16 v[108:111], v[164:167], v[196:199], v[108:111]
	v_mfma_f32_16x16x32_bf16 v[104:107], v[172:175], v[196:199], v[104:107]
	v_mfma_f32_16x16x32_bf16 v[92:95], v[164:167], v[214:217], v[92:95]
	v_mfma_f32_16x16x32_bf16 v[88:91], v[172:175], v[214:217], v[88:91]
	v_mfma_f32_16x16x32_bf16 v[76:79], v[164:167], v[222:225], v[76:79]
	v_mfma_f32_16x16x32_bf16 v[72:75], v[172:175], v[222:225], v[72:75]
	v_mfma_f32_16x16x32_bf16 v[124:127], v[168:171], v[192:195], v[124:127]
	v_mfma_f32_16x16x32_bf16 v[120:123], v[184:187], v[192:195], v[120:123]
	v_mfma_f32_16x16x32_bf16 v[108:111], v[168:171], v[200:203], v[108:111]
	v_mfma_f32_16x16x32_bf16 v[104:107], v[184:187], v[200:203], v[104:107]
	v_mfma_f32_16x16x32_bf16 v[92:95], v[168:171], v[218:221], v[92:95]
	v_mfma_f32_16x16x32_bf16 v[88:91], v[184:187], v[218:221], v[88:91]
	v_mfma_f32_16x16x32_bf16 v[76:79], v[168:171], v[226:229], v[76:79]
	v_mfma_f32_16x16x32_bf16 v[72:75], v[184:187], v[226:229], v[72:75]
	s_setprio 0
	s_barrier
	s_add_i32 s36, s72, s20
	s_mov_b32 m0, s36
	global_load_lds_dwordx4 v34, s[98:99]
	s_add_i32 m0, s36, 0x2000
	s_add_u32 s36, s44, 0x160080
	s_addc_u32 s37, s45, 0
	s_add_i32 s44, s73, s20
	global_load_lds_dwordx4 v142, s[98:99]
	s_mov_b32 m0, s44
	s_nop 0
	global_load_lds_dwordx4 v34, s[36:37]
	s_add_i32 m0, s44, 0x2000
	s_nop 0
	global_load_lds_dwordx4 v142, s[36:37]
	s_mov_b32 m0, s50
	s_nop 0
	global_load_lds_dwordx4 v14, s[100:101]
	s_mov_b32 m0, s51
	s_nop 0
	global_load_lds_dwordx4 v140, s[100:101]
	ds_read_b128 v[188:191], v155 offset:49152
	ds_read_b128 v[192:195], v155 offset:50176
	ds_read_b128 v[196:199], v155 offset:51200
	ds_read_b128 v[200:203], v155 offset:52224
	ds_read_b128 v[214:217], v155 offset:53248
	ds_read_b128 v[218:221], v155 offset:54272
	ds_read_b128 v[222:225], v155 offset:55296
	ds_read_b128 v[226:229], v155 offset:56320
	s_waitcnt vmcnt(8)
	s_waitcnt lgkmcnt(0)
	s_barrier
	s_setprio 1
	s_waitcnt lgkmcnt(0)
	v_mfma_f32_16x16x32_bf16 v[68:71], v[136:139], v[188:191], v[68:71]
	v_mfma_f32_16x16x32_bf16 v[64:67], v[156:159], v[188:191], v[64:67]
	v_mfma_f32_16x16x32_bf16 v[52:55], v[136:139], v[196:199], v[52:55]
	v_mfma_f32_16x16x32_bf16 v[48:51], v[156:159], v[196:199], v[48:51]
	v_mfma_f32_16x16x32_bf16 v[36:39], v[136:139], v[214:217], v[36:39]
	v_mfma_f32_16x16x32_bf16 v[30:33], v[156:159], v[214:217], v[30:33]
	v_mfma_f32_16x16x32_bf16 v[18:21], v[136:139], v[222:225], v[18:21]
	v_mfma_f32_16x16x32_bf16 v[10:13], v[156:159], v[222:225], v[10:13]
	v_mfma_f32_16x16x32_bf16 v[68:71], v[148:151], v[192:195], v[68:71]
	v_mfma_f32_16x16x32_bf16 v[64:67], v[160:163], v[192:195], v[64:67]
	v_mfma_f32_16x16x32_bf16 v[52:55], v[148:151], v[200:203], v[52:55]
	v_mfma_f32_16x16x32_bf16 v[48:51], v[160:163], v[200:203], v[48:51]
	v_mfma_f32_16x16x32_bf16 v[36:39], v[148:151], v[218:221], v[36:39]
	v_mfma_f32_16x16x32_bf16 v[30:33], v[160:163], v[218:221], v[30:33]
	v_mfma_f32_16x16x32_bf16 v[18:21], v[148:151], v[226:229], v[18:21]
	v_mfma_f32_16x16x32_bf16 v[10:13], v[160:163], v[226:229], v[10:13]
	s_setprio 0
	s_setprio 1
	v_mfma_f32_16x16x32_bf16 v[60:63], v[164:167], v[188:191], v[60:63]
	v_mfma_f32_16x16x32_bf16 v[56:59], v[172:175], v[188:191], v[56:59]
	v_mfma_f32_16x16x32_bf16 v[44:47], v[164:167], v[196:199], v[44:47]
	v_mfma_f32_16x16x32_bf16 v[40:43], v[172:175], v[196:199], v[40:43]
	v_mfma_f32_16x16x32_bf16 v[26:29], v[164:167], v[214:217], v[26:29]
	v_mfma_f32_16x16x32_bf16 v[22:25], v[172:175], v[214:217], v[22:25]
	v_mfma_f32_16x16x32_bf16 v[6:9], v[164:167], v[222:225], v[6:9]
	v_mfma_f32_16x16x32_bf16 v[2:5], v[172:175], v[222:225], v[2:5]
	v_mfma_f32_16x16x32_bf16 v[60:63], v[168:171], v[192:195], v[60:63]
	v_mfma_f32_16x16x32_bf16 v[56:59], v[184:187], v[192:195], v[56:59]
	v_mfma_f32_16x16x32_bf16 v[44:47], v[168:171], v[200:203], v[44:47]
	v_mfma_f32_16x16x32_bf16 v[40:43], v[184:187], v[200:203], v[40:43]
	v_mfma_f32_16x16x32_bf16 v[26:29], v[168:171], v[218:221], v[26:29]
	v_mfma_f32_16x16x32_bf16 v[22:25], v[184:187], v[218:221], v[22:25]
	v_mfma_f32_16x16x32_bf16 v[6:9], v[168:171], v[226:229], v[6:9]
	v_mfma_f32_16x16x32_bf16 v[2:5], v[184:187], v[226:229], v[2:5]
	s_setprio 0
	s_barrier
	s_add_u32 s70, s70, 0x100
	s_addc_u32 s71, s71, 0
	s_cmp_ge_i32 vcc_lo, s67
	s_mov_b64 s[36:37], s[42:43]
	s_mov_b32 s44, vcc_lo
	s_cbranch_scc0 .LBB0_1764
	s_mov_b32 s71, 0x200000
	s_and_b64 vcc, exec, s[8:9]
	s_cbranch_vccz .LBB0_1767
